# prep waves: 6 in-place v_sub pairs packed into v_pk_add_f32 (even-register broadcast form) + one copy dropped in the prep-Y xor16 reduction; on top of v38
# baseline (speedup 1.0000x reference)
; #define LAS __attribute__((address_space(3)))
; #define ZERO_ENDS4(A) do { if (!pz) A[1] = (u32x4){0u, 0u, 0u, 0u}; if (!nz) A[2] = (u32x4){0u, 0u, 0u, 0u}; } while (0)
; __device__ __forceinline__ void prep_y(int l, int b, int h, int dir, int c, LAS float* rg, const LAS float* cst, int lane) {
;     PREP_COMMON();
;     const bf16* Wi = (const bf16*)(ws + OFF_WIC) + (size_t)dir * DM * 64;
;     u32x4 cir[2][3];
; #pragma unroll
;     for (int ks = 0; ks < 2; ++ks) { const bf16* q = rawA + 3200 + 64 * dir + 32 * ks + 8 * fq; cir[ks][0] = *(const u32x4*)q; cir[ks][1] = *(const u32x4*)(q + dp); cir[ks][2] = *(const u32x4*)(q + dn); }
;     u32x4 wir[4][2]; u32x2 kr[4][3], rr_[4][3];
; #pragma unroll
;     for (int nb = 0; nb < 4; ++nb) { const int chr = h * 64 + nb * 16 + fr;
; #pragma unroll
;         for (int ks = 0; ks < 2; ++ks) wir[nb][ks] = *(const u32x4*)(Wi + (size_t)chr * 64 + 32 * ks + 8 * fq);
;         const bf16* q = rawA + h * 64 + nb * 16 + 4 * fq;
;         rr_[nb][0] = *(const u32x2*)q; rr_[nb][1] = *(const u32x2*)(q + dp); rr_[nb][2] = *(const u32x2*)(q + dn);
;         kr[nb][0] = *(const u32x2*)(q + 1024); kr[nb][1] = *(const u32x2*)(q + 1024 + dp); kr[nb][2] = *(const u32x2*)(q + 1024 + dn); }
;     __builtin_amdgcn_sched_barrier(0);
;     bf16x8 bi[2];
; #pragma unroll
;     for (int ks = 0; ks < 2; ++ks) {
;         float o[8]; const int cc = 128 + 64 * dir + 32 * ks + 8 * fq;
;         ZERO_ENDS4(cir[ks]);
;         mix8p(cir[ks][0], cir[ks][1], cir[ks][2], cst + C_CMP + cc, cst + C_CMN + cc, o);
.LBB0_370:
	s_cmpk_eq_i32 s81, 0x7f
	s_cbranch_scc1 .LBB0_424
	s_add_i32 s6, s81, 1
	s_lshl_b32 s7, s6, 1
	s_and_b32 s7, s7, 2
	s_or_b32 s7, s7, s87
	s_mulk_i32 s7, 0x4100
	s_add_i32 s82, s7, 0
	s_lshl_b32 s83, s6, 4
	s_mov_b64 s[6:7], -1
	s_and_b64 vcc, exec, s[94:95]
	s_cbranch_vccz .LBB0_375
	s_mov_b64 s[6:7], s[0:1]
	s_load_dwordx2 s[52:53], s[6:7], 0xb8
	v_mov_b32_e32 v144, v160
	s_lshl_b32 s96, s8, 1
	v_and_b32_e32 v145, 15, v144
	v_or_b32_e32 v2, s83, v145
	v_sub_u32_e32 v4, 0x7ff, v2
	v_cndmask_b32_e64 v2, v4, v2, s[38:39]
	v_lshl_add_u64 v[4:5], s[30:31], 0, v[2:3]
	s_waitcnt lgkmcnt(0)
	v_mov_b64_e32 v[10:11], s[52:53]
	v_ashrrev_i32_e32 v46, 4, v144
	v_mad_u64_u32 v[10:11], s[6:7], v4, s22, v[10:11]
	v_mad_i32_i24 v11, v5, s22, v11
	v_lshlrev_b32_e32 v32, 3, v46
	v_lshl_add_u64 v[10:11], v[10:11], 0, s[12:13]
	v_ashrrev_i32_e32 v33, 31, v32
	v_lshl_add_u64 v[20:21], v[10:11], 0, s[96:97]
	v_lshlrev_b64 v[26:27], 1, v[32:33]
	v_lshl_add_u64 v[20:21], v[20:21], 0, v[26:27]
	s_mov_b64 s[6:7], 0x1900
	v_cmp_eq_u32_e32 vcc, 0, v2
	v_cmp_gt_u32_e64 s[48:49], s24, v2
	v_lshl_add_u64 v[40:41], v[20:21], 0, s[6:7]
	v_add_co_u32_e64 v20, s[50:51], s25, v20
	s_add_u32 s6, s52, s5
	v_cndmask_b32_e64 v15, -1, 0, vcc
	v_cndmask_b32_e64 v14, v203, 0, vcc
	v_cndmask_b32_e64 v2, 0, v202, s[48:49]
	v_addc_co_u32_e64 v21, s[50:51], 0, v21, s[50:51]
	s_addc_u32 s7, s53, 0
	v_lshl_add_u64 v[42:43], v[40:41], 0, v[14:15]
	v_lshl_add_u64 v[44:45], v[40:41], 0, v[2:3]
	global_load_dwordx4 v[48:51], v[20:21], off offset:2304
	global_load_dwordx4 v[52:55], v[40:41], off offset:64
	global_load_dwordx4 v[108:111], v[42:43], off
	global_load_dwordx4 v[112:115], v[42:43], off offset:64
	global_load_dwordx4 v[146:149], v[44:45], off
	global_load_dwordx4 v[150:153], v[44:45], off offset:64
	v_lshl_add_u64 v[20:21], s[6:7], 0, v[26:27]
	s_mov_b32 s35, s97
	v_lshlrev_b32_e32 v26, 2, v46
	v_lshl_add_u64 v[10:11], v[10:11], 0, s[34:35]
	v_ashrrev_i32_e32 v27, 31, v26
	v_lshl_add_u64 v[26:27], v[26:27], 1, v[10:11]
	v_or_b32_e32 v10, s56, v145
	v_lshlrev_b32_e32 v10, 7, v10
	v_mov_b32_e32 v11, v3
	v_lshl_add_u64 v[10:11], v[20:21], 0, v[10:11]
	s_mov_b64 s[6:7], 0x1b40000
	v_lshl_add_u64 v[20:21], v[10:11], 0, s[6:7]
	s_mov_b32 s6, 0x1b41000
	v_add_co_u32_e64 v10, s[50:51], s6, v10
	v_lshl_add_u64 v[74:75], v[26:27], 0, v[14:15]
	s_nop 0
	v_addc_co_u32_e64 v11, s[50:51], 0, v11, s[50:51]
	v_lshl_add_u64 v[134:135], v[26:27], 0, v[2:3]
	global_load_dwordx4 v[76:79], v[20:21], off offset:64
	global_load_dwordx4 v[68:71], v[20:21], off offset:2048
	global_load_dwordx2 v[130:131], v[74:75], off
	global_load_dwordx4 v[64:67], v[20:21], off offset:2112
	global_load_dwordx4 v[80:83], v[10:11], off offset:-4096
	global_load_dwordx4 v[60:63], v[10:11], off
	global_load_dwordx4 v[56:59], v[10:11], off offset:64
	global_load_dwordx4 v[44:47], v[10:11], off offset:2048
	global_load_dwordx4 v[40:43], v[10:11], off offset:2112
	global_load_dwordx2 v[116:117], v[26:27], off
	global_load_dwordx2 v[96:97], v[26:27], off offset:32
	global_load_dwordx2 v[86:87], v[26:27], off offset:64
	s_nop 0
	global_load_dwordx2 v[10:11], v[26:27], off offset:96
	global_load_dwordx2 v[138:139], v[74:75], off offset:2048
	global_load_dwordx2 v[98:99], v[74:75], off offset:32
	global_load_dwordx2 v[88:89], v[74:75], off offset:64
	global_load_dwordx2 v[14:15], v[74:75], off offset:96
	global_load_dwordx2 v[142:143], v[134:135], off offset:2048
	global_load_dwordx2 v[100:101], v[134:135], off offset:32
	global_load_dwordx2 v[90:91], v[134:135], off offset:64
	global_load_dwordx2 v[20:21], v[134:135], off offset:96
	global_load_dwordx2 v[72:73], v[26:27], off offset:2048
	global_load_dwordx2 v[102:103], v[26:27], off offset:2080
	global_load_dwordx2 v[92:93], v[26:27], off offset:2112
	s_nop 0
	global_load_dwordx2 v[26:27], v[26:27], off offset:2144
	s_nop 0
	global_load_dwordx2 v[132:133], v[134:135], off
	global_load_dwordx2 v[104:105], v[74:75], off offset:2080
	global_load_dwordx2 v[94:95], v[74:75], off offset:2112
	global_load_dwordx2 v[84:85], v[74:75], off offset:2144
	global_load_dwordx2 v[106:107], v[134:135], off offset:2080
	global_load_dwordx2 v[136:137], v[134:135], off offset:2112
	global_load_dwordx2 v[140:141], v[134:135], off offset:2144
	v_mov_b32_e32 v2, s82
	v_mad_u32_u24 v33, v145, s72, v2
	v_add_u32_e32 v2, s9, v32
	v_lshl_add_u32 v2, v2, 2, 0
	s_waitcnt vmcnt(35)
	v_cndmask_b32_e64 v135, v108, 0, vcc
	v_add_u32_e32 v170, 0x24800, v2
	v_cndmask_b32_e64 v74, v111, 0, vcc
	v_cndmask_b32_e64 v75, v110, 0, vcc
	v_cndmask_b32_e64 v134, v109, 0, vcc
	s_waitcnt vmcnt(33)
	v_cndmask_b32_e64 v145, 0, v149, s[48:49]
	v_cndmask_b32_e64 v158, 0, v148, s[48:49]
	v_cndmask_b32_e64 v159, 0, v147, s[48:49]
	v_cndmask_b32_e64 v168, 0, v146, s[48:49]
	v_add_u32_e32 v2, 0x24c00, v2
	ds_read_b128 v[108:111], v170
	ds_read_b128 v[146:149], v170 offset:16
	ds_read_b128 v[154:157], v2
	ds_read_b128 v[224:227], v2 offset:16
	v_lshlrev_b32_e32 v171, 16, v48
	v_lshlrev_b32_e32 v228, 16, v135
	v_lshlrev_b32_e32 v219, 16, v168
	v_sub_f32_e32 v228, v228, v171
	v_and_b32_e32 v48, 0xffff0000, v48
	v_and_b32_e32 v135, 0xffff0000, v135
	v_sub_f32_e32 v219, v219, v171
	s_waitcnt lgkmcnt(3)
	v_fmac_f32_e32 v171, v108, v228
	v_and_b32_e32 v108, 0xffff0000, v168
	v_sub_f32_e32 v135, v135, v48
	v_sub_f32_e32 v108, v108, v48
	v_fmac_f32_e32 v48, v109, v135
	s_waitcnt lgkmcnt(1)
; #define LAS __attribute__((address_space(3)))
; __device__ __forceinline__ bf16x8 pack8(const float* f) { return __builtin_bit_cast(bf16x8, pack8u(f)); }
; #define ZERO_ENDS4(A) do { if (!pz) A[1] = (u32x4){0u, 0u, 0u, 0u}; if (!nz) A[2] = (u32x4){0u, 0u, 0u, 0u}; } while (0)
; #define ZERO_ENDS2(A) do { if (!pz) A[1] = (u32x2){0u, 0u}; if (!nz) A[2] = (u32x2){0u, 0u}; } while (0)
; __device__ __forceinline__ void prep_y(int l, int b, int h, int dir, int c, LAS float* rg, const LAS float* cst, int lane) {
;     ...
;     bf16x8 bi[2];
; #pragma unroll
;     for (int ks = 0; ks < 2; ++ks) {
;         float o[8]; const int cc = 128 + 64 * dir + 32 * ks + 8 * fq;
;         ZERO_ENDS4(cir[ks]);
;         mix8p(cir[ks][0], cir[ks][1], cir[ks][2], cst + C_CMP + cc, cst + C_CMN + cc, o);
;         bi[ks] = pack8(o);
;     }
;     float kk[16]; float ss = 0.f;
; #pragma unroll
;     for (int nb = 0; nb < 4; ++nb) {
;         const int co = nb * 16 + 4 * fq;
;         ZERO_ENDS2(kr[nb]);
;         mix4p(kr[nb][0], kr[nb][1], kr[nb][2], cst + C_RMP + 64 + co, cst + C_RMN + 64 + co, kk + 4 * nb);
;         const f32x4 kkw = *(const LAS f32x4*)(cst + C_KK + co);
; #pragma unroll
;         for (int i = 0; i < 4; ++i) { const float kr_ = kk[4 * nb + i] * kkw[i]; ss += kr_ * kr_; }
	v_fmac_f32_e32 v48, v155, v108
	v_lshlrev_b32_e32 v108, 16, v49
	v_lshlrev_b32_e32 v135, 16, v134
	v_lshlrev_b32_e32 v109, 16, v159
	v_sub_f32_e32 v135, v135, v108
	v_sub_f32_e32 v109, v109, v108
	v_fmac_f32_e32 v108, v110, v135
	v_and_b32_e32 v49, 0xffff0000, v49
	v_and_b32_e32 v110, 0xffff0000, v134
	v_fmac_f32_e32 v108, v156, v109
	v_and_b32_e32 v109, 0xffff0000, v159
	v_sub_f32_e32 v110, v110, v49
	v_sub_f32_e32 v109, v109, v49
	v_fmac_f32_e32 v49, v111, v110
	v_fmac_f32_e32 v49, v157, v109
	v_lshlrev_b32_e32 v109, 16, v50
	v_lshlrev_b32_e32 v111, 16, v75
	v_lshlrev_b32_e32 v110, 16, v158
	v_sub_f32_e32 v111, v111, v109
	v_sub_f32_e32 v110, v110, v109
	v_fmac_f32_e32 v109, v146, v111
	v_and_b32_e32 v50, 0xffff0000, v50
	v_and_b32_e32 v75, 0xffff0000, v75
	s_waitcnt lgkmcnt(0)
	v_fmac_f32_e32 v109, v224, v110
	v_and_b32_e32 v110, 0xffff0000, v158
	v_sub_f32_e32 v75, v75, v50
	v_sub_f32_e32 v110, v110, v50
	v_fmac_f32_e32 v50, v147, v75
	v_lshlrev_b32_e32 v75, 16, v51
	v_lshlrev_b32_e32 v111, 16, v74
	v_fmac_f32_e32 v50, v225, v110
	v_lshlrev_b32_e32 v110, 16, v145
	v_sub_f32_e32 v111, v111, v75
	v_sub_f32_e32 v110, v110, v75
	v_fmac_f32_e32 v75, v148, v111
	v_and_b32_e32 v51, 0xffff0000, v51
	v_and_b32_e32 v74, 0xffff0000, v74
	v_fmac_f32_e32 v75, v226, v110
	v_and_b32_e32 v110, 0xffff0000, v145
	v_sub_f32_e32 v74, v74, v51
	v_sub_f32_e32 v110, v110, v51
	v_fmac_f32_e32 v51, v149, v74
	v_fmac_f32_e32 v51, v227, v110
	v_cndmask_b32_e64 v135, v112, 0, vcc
	v_fmac_f32_e32 v171, v154, v219
	v_cvt_pk_bf16_f32 v49, v108, v49
	v_cvt_pk_bf16_f32 v50, v109, v50
	v_cvt_pk_bf16_f32 v51, v75, v51
	v_cndmask_b32_e64 v74, v115, 0, vcc
	v_cndmask_b32_e64 v75, v114, 0, vcc
	v_cndmask_b32_e64 v134, v113, 0, vcc
	s_waitcnt vmcnt(32)
	v_cndmask_b32_e64 v145, 0, v153, s[48:49]
	v_cndmask_b32_e64 v154, 0, v152, s[48:49]
	v_cndmask_b32_e64 v155, 0, v151, s[48:49]
	v_cndmask_b32_e64 v156, 0, v150, s[48:49]
	ds_read_b128 v[108:111], v170 offset:128
	ds_read_b128 v[112:115], v170 offset:144
	ds_read_b128 v[146:149], v2 offset:128
	ds_read_b128 v[150:153], v2 offset:144
	v_lshlrev_b32_e32 v2, 16, v52
	v_lshlrev_b32_e32 v158, 16, v135
	v_lshlrev_b32_e32 v157, 16, v156
	v_sub_f32_e32 v158, v158, v2
	v_and_b32_e32 v52, 0xffff0000, v52
	v_and_b32_e32 v135, 0xffff0000, v135
	v_sub_f32_e32 v157, v157, v2
	s_waitcnt lgkmcnt(3)
	v_fmac_f32_e32 v2, v108, v158
	v_and_b32_e32 v108, 0xffff0000, v156
	v_sub_f32_e32 v135, v135, v52
	v_sub_f32_e32 v108, v108, v52
	v_fmac_f32_e32 v52, v109, v135
	s_waitcnt lgkmcnt(1)
	v_fmac_f32_e32 v52, v147, v108
	v_lshlrev_b32_e32 v108, 16, v53
	v_lshlrev_b32_e32 v135, 16, v134
	v_lshlrev_b32_e32 v109, 16, v155
	v_sub_f32_e32 v135, v135, v108
	v_sub_f32_e32 v109, v109, v108
	v_fmac_f32_e32 v108, v110, v135
	v_and_b32_e32 v53, 0xffff0000, v53
	v_and_b32_e32 v110, 0xffff0000, v134
	v_fmac_f32_e32 v108, v148, v109
	v_and_b32_e32 v109, 0xffff0000, v155
	v_sub_f32_e32 v110, v110, v53
	v_sub_f32_e32 v109, v109, v53
	v_fmac_f32_e32 v53, v111, v110
	v_fmac_f32_e32 v53, v149, v109
	v_lshlrev_b32_e32 v109, 16, v54
	v_lshlrev_b32_e32 v111, 16, v75
	v_lshlrev_b32_e32 v110, 16, v154
	v_sub_f32_e32 v111, v111, v109
	v_sub_f32_e32 v110, v110, v109
	v_fmac_f32_e32 v109, v112, v111
	v_and_b32_e32 v54, 0xffff0000, v54
	v_and_b32_e32 v75, 0xffff0000, v75
	s_waitcnt lgkmcnt(0)
	v_fmac_f32_e32 v109, v150, v110
	v_and_b32_e32 v110, 0xffff0000, v154
	v_sub_f32_e32 v75, v75, v54
	v_sub_f32_e32 v110, v110, v54
	v_fmac_f32_e32 v54, v113, v75
	v_lshlrev_b32_e32 v75, 16, v55
	v_lshlrev_b32_e32 v111, 16, v74
	v_fmac_f32_e32 v54, v151, v110
	v_lshlrev_b32_e32 v110, 16, v145
	v_sub_f32_e32 v111, v111, v75
	v_sub_f32_e32 v110, v110, v75
	v_fmac_f32_e32 v75, v114, v111
	v_and_b32_e32 v55, 0xffff0000, v55
	v_and_b32_e32 v74, 0xffff0000, v74
	v_and_b32_e32 v147, -16, v144
	v_fmac_f32_e32 v75, v152, v110
	v_and_b32_e32 v110, 0xffff0000, v145
	v_sub_f32_e32 v74, v74, v55
	v_cvt_pk_bf16_f32 v54, v109, v54
	v_add_u32_e32 v109, 0, v147
	v_sub_f32_e32 v110, v110, v55
	v_fmac_f32_e32 v55, v115, v74
	v_add_u32_e32 v111, 0x25100, v109
	v_fmac_f32_e32 v55, v153, v110
	v_add_u32_e32 v113, 0x25400, v109
	ds_read_b128 v[148:151], v111
	ds_read_b128 v[152:155], v113
	s_waitcnt vmcnt(18)
	v_cndmask_b32_e64 v74, v138, 0, vcc
	v_cvt_pk_bf16_f32 v53, v108, v53
	s_waitcnt vmcnt(14)
	v_cndmask_b32_e64 v108, 0, v142, s[48:49]
	s_waitcnt vmcnt(10)
	v_lshlrev_b32_e32 v110, 16, v72
	v_lshlrev_b32_e32 v114, 16, v74
	v_lshlrev_b32_e32 v112, 16, v108
	v_sub_f32_e32 v114, v114, v110
	v_fmac_f32_e32 v2, v146, v157
	v_sub_f32_e32 v112, v112, v110
	s_waitcnt lgkmcnt(1)
	v_fmac_f32_e32 v110, v148, v114
	s_waitcnt lgkmcnt(0)
	v_fmac_f32_e32 v110, v152, v112
	v_and_b32_e32 v112, 0xffff0000, v72
	v_and_b32_e32 v74, 0xffff0000, v74
	v_cvt_pk_bf16_f32 v52, v2, v52
	v_cndmask_b32_e64 v2, v139, 0, vcc
	v_and_b32_e32 v72, 0xffff0000, v108
	v_sub_f32_e32 v74, v74, v112
	v_cvt_pk_bf16_f32 v55, v75, v55
	v_cndmask_b32_e64 v75, 0, v143, s[48:49]
	v_sub_f32_e32 v72, v72, v112
	v_fmac_f32_e32 v112, v149, v74
	v_lshlrev_b32_e32 v114, 16, v73
	v_lshlrev_b32_e32 v74, 16, v2
	v_fmac_f32_e32 v112, v153, v72
	v_lshlrev_b32_e32 v72, 16, v75
	v_sub_f32_e32 v74, v74, v114
	v_sub_f32_e32 v72, v72, v114
	v_fmac_f32_e32 v114, v150, v74
	v_and_b32_e32 v108, 0xffff0000, v73
	v_and_b32_e32 v2, 0xffff0000, v2
	v_fmac_f32_e32 v114, v154, v72
	v_and_b32_e32 v72, 0xffff0000, v75
	v_sub_f32_e32 v2, v2, v108
	v_sub_f32_e32 v72, v72, v108
	v_fmac_f32_e32 v108, v151, v2
	v_add_u32_e32 v2, 0x25a00, v109
	v_fmac_f32_e32 v108, v155, v72
	ds_read_b128 v[72:75], v2
	ds_read_b128 v[148:151], v111 offset:64
	ds_read_b128 v[152:155], v113 offset:64
	s_waitcnt vmcnt(5)
; #define LAS __attribute__((address_space(3)))
; #define MFMA16(a, b, c) __builtin_amdgcn_mfma_f32_16x16x32_bf16((a), (b), (c), 0, 0, 0)
; #define ZERO_ENDS2(A) do { if (!pz) A[1] = (u32x2){0u, 0u}; if (!nz) A[2] = (u32x2){0u, 0u}; } while (0)
; __device__ __forceinline__ void prep_y(int l, int b, int h, int dir, int c, LAS float* rg, const LAS float* cst, int lane) {
;     ...
; #pragma unroll
;     for (int nb = 0; nb < 4; ++nb) {
;         const int co = nb * 16 + 4 * fq;
;         ZERO_ENDS2(kr[nb]);
;         mix4p(kr[nb][0], kr[nb][1], kr[nb][2], cst + C_RMP + 64 + co, cst + C_RMN + 64 + co, kk + 4 * nb);
;         const f32x4 kkw = *(const LAS f32x4*)(cst + C_KK + co);
; #pragma unroll
;         for (int i = 0; i < 4; ++i) { const float kr_ = kk[4 * nb + i] * kkw[i]; ss += kr_ * kr_; }
;     }
;     ss += __shfl_xor(ss, 16); ss += __shfl_xor(ss, 32);
;     const float nrm = rsqrtf(ss + 1e-12f);
;     float cs = 0.f;
; #pragma unroll
;     for (int nb = 0; nb < 4; ++nb) {
;         f32x4 aI = {0.f, 0.f, 0.f, 0.f};
; #pragma unroll
;         for (int ks = 0; ks < 2; ++ks) aI = MFMA16(__builtin_bit_cast(bf16x8, wir[nb][ks]), bi[ks], aI);
;         const int co = nb * 16 + 4 * fq;
;         float rr[4];
;         ZERO_ENDS2(rr_[nb]);
;         mix4p(rr_[nb][0], rr_[nb][1], rr_[nb][2], cst + C_RMP + co, cst + C_RMN + co, rr);
	v_cndmask_b32_e64 v115, v104, 0, vcc
	s_waitcnt vmcnt(2)
	v_cndmask_b32_e64 v134, 0, v106, s[48:49]
	v_lshlrev_b32_e32 v106, 16, v102
	v_lshlrev_b32_e32 v135, 16, v115
	v_lshlrev_b32_e32 v104, 16, v134
	v_sub_f32_e32 v135, v135, v106
	v_sub_f32_e32 v104, v104, v106
	s_waitcnt lgkmcnt(1)
	v_fmac_f32_e32 v106, v148, v135
	s_waitcnt lgkmcnt(0)
	v_fmac_f32_e32 v106, v152, v104
	v_and_b32_e32 v104, 0xffff0000, v102
	v_and_b32_e32 v115, 0xffff0000, v115
	v_and_b32_e32 v102, 0xffff0000, v134
	v_sub_f32_e32 v115, v115, v104
	v_cndmask_b32_e64 v105, v105, 0, vcc
	v_sub_f32_e32 v102, v102, v104
	v_fmac_f32_e32 v104, v149, v115
	v_cndmask_b32_e64 v107, 0, v107, s[48:49]
	v_fmac_f32_e32 v104, v153, v102
	v_lshlrev_b32_e32 v102, 16, v103
	v_lshlrev_b32_e32 v134, 16, v105
	v_and_b32_e32 v103, 0xffff0000, v103
	v_and_b32_e32 v105, 0xffff0000, v105
	v_lshlrev_b32_e32 v115, 16, v107
	v_sub_f32_e32 v134, v134, v102
	v_and_b32_e32 v107, 0xffff0000, v107
	v_sub_f32_e32 v105, v105, v103
	v_sub_f32_e32 v115, v115, v102
	v_fmac_f32_e32 v102, v150, v134
	v_sub_f32_e32 v107, v107, v103
	v_fmac_f32_e32 v103, v151, v105
	ds_read_b128 v[148:151], v2 offset:64
	v_fmac_f32_e32 v102, v154, v115
	v_fmac_f32_e32 v103, v155, v107
	s_waitcnt vmcnt(1)
	v_cndmask_b32_e64 v143, 0, v137, s[48:49]
	s_waitcnt lgkmcnt(0)
	v_mul_f32_e32 v107, v106, v148
	v_mul_f32_e32 v105, v104, v149
	v_pk_mul_f32 v[134:135], v[102:103], v[150:151]
	v_cndmask_b32_e64 v145, 0, v136, s[48:49]
	ds_read_b128 v[136:139], v111 offset:128
	ds_read_b128 v[148:151], v113 offset:128
	v_cndmask_b32_e64 v142, v94, 0, vcc
	v_lshlrev_b32_e32 v94, 16, v92
	v_lshlrev_b32_e32 v146, 16, v142
	v_cndmask_b32_e64 v115, v95, 0, vcc
	v_lshlrev_b32_e32 v95, 16, v145
	v_sub_f32_e32 v146, v146, v94
	v_sub_f32_e32 v95, v95, v94
	s_waitcnt lgkmcnt(1)
	v_fmac_f32_e32 v94, v136, v146
	s_waitcnt lgkmcnt(0)
	v_fmac_f32_e32 v94, v148, v95
	v_and_b32_e32 v95, 0xffff0000, v92
	v_and_b32_e32 v136, 0xffff0000, v142
	v_and_b32_e32 v92, 0xffff0000, v145
	v_sub_f32_e32 v136, v136, v95
	v_sub_f32_e32 v92, v92, v95
	v_fmac_f32_e32 v95, v137, v136
	v_fmac_f32_e32 v95, v149, v92
	v_lshlrev_b32_e32 v92, 16, v93
	v_lshlrev_b32_e32 v137, 16, v115
	v_lshlrev_b32_e32 v136, 16, v143
	s_nop 0
	v_pk_add_f32 v[136:137], v[136:137], v[92:93] op_sel_hi:[1,0] neg_lo:[0,1] neg_hi:[0,1]
	v_fmac_f32_e32 v92, v138, v137
	v_and_b32_e32 v93, 0xffff0000, v93
	v_and_b32_e32 v115, 0xffff0000, v115
	v_fmac_f32_e32 v92, v150, v136
	v_and_b32_e32 v136, 0xffff0000, v143
	v_sub_f32_e32 v115, v115, v93
	v_sub_f32_e32 v136, v136, v93
	v_fmac_f32_e32 v93, v139, v115
	v_fmac_f32_e32 v93, v151, v136
	ds_read_b128 v[136:139], v2 offset:128
	s_waitcnt vmcnt(0)
	v_cndmask_b32_e64 v146, 0, v141, s[48:49]
	v_cndmask_b32_e64 v152, 0, v140, s[48:49]
	ds_read_b128 v[140:143], v111 offset:192
	ds_read_b128 v[148:151], v113 offset:192
	v_cndmask_b32_e64 v145, v84, 0, vcc
	v_lshlrev_b32_e32 v84, 16, v26
	v_lshlrev_b32_e32 v111, 16, v145
	v_cndmask_b32_e64 v115, v85, 0, vcc
	v_lshlrev_b32_e32 v85, 16, v152
	v_sub_f32_e32 v111, v111, v84
	v_sub_f32_e32 v85, v85, v84
	s_waitcnt lgkmcnt(1)
	v_fmac_f32_e32 v84, v140, v111
	s_waitcnt lgkmcnt(0)
	v_fmac_f32_e32 v84, v148, v85
	v_and_b32_e32 v85, 0xffff0000, v26
	v_and_b32_e32 v111, 0xffff0000, v145
	v_and_b32_e32 v26, 0xffff0000, v152
	v_sub_f32_e32 v111, v111, v85
	v_sub_f32_e32 v26, v26, v85
	v_fmac_f32_e32 v85, v141, v111
	v_fmac_f32_e32 v85, v149, v26
	v_lshlrev_b32_e32 v26, 16, v27
	v_lshlrev_b32_e32 v113, 16, v115
	v_lshlrev_b32_e32 v111, 16, v146
	v_sub_f32_e32 v113, v113, v26
	v_sub_f32_e32 v111, v111, v26
	v_fmac_f32_e32 v26, v142, v113
	v_and_b32_e32 v27, 0xffff0000, v27
	v_and_b32_e32 v113, 0xffff0000, v115
	v_fmac_f32_e32 v26, v150, v111
	v_and_b32_e32 v111, 0xffff0000, v146
	v_sub_f32_e32 v113, v113, v27
	v_sub_f32_e32 v111, v111, v27
	v_fmac_f32_e32 v27, v143, v113
	v_and_b32_e32 v113, 64, v198
	v_cvt_pk_bf16_f32 v48, v171, v48
	v_fmac_f32_e32 v27, v151, v111
	v_xor_b32_e32 v111, 16, v198
	v_add_u32_e32 v113, 64, v113
	v_cmp_lt_i32_e64 s[50:51], v111, v113
	v_mfma_f32_16x16x32_bf16 v[80:83], v[80:83], v[48:51], 0
	ds_read_b128 v[140:143], v2 offset:192
	v_cndmask_b32_e64 v111, v198, v111, s[50:51]
	v_lshlrev_b32_e32 v146, 2, v111
	v_xor_b32_e32 v111, 32, v198
	v_cmp_lt_i32_e64 s[50:51], v111, v113
	v_mfma_f32_16x16x32_bf16 v[148:151], v[76:79], v[52:55], v[80:83]
	v_cndmask_b32_e64 v113, 0, v132, s[48:49]
	v_cndmask_b32_e64 v111, v198, v111, s[50:51]
	v_lshlrev_b32_e32 v145, 2, v111
	v_add_u32_e32 v82, 0x25000, v109
	v_cndmask_b32_e64 v80, v131, 0, vcc
	v_cndmask_b32_e64 v81, v130, 0, vcc
	v_cndmask_b32_e64 v111, 0, v133, s[48:49]
	v_add_u32_e32 v83, 0x25300, v109
	ds_read_b128 v[76:79], v82
	ds_read_b128 v[130:133], v83
	v_lshlrev_b32_e32 v170, 16, v116
	v_lshlrev_b32_e32 v152, 16, v81
	v_lshlrev_b32_e32 v115, 16, v113
	v_sub_f32_e32 v152, v152, v170
	v_and_b32_e32 v171, 0xffff0000, v116
	v_and_b32_e32 v81, 0xffff0000, v81
	v_sub_f32_e32 v115, v115, v170
	s_waitcnt lgkmcnt(1)
	v_fmac_f32_e32 v170, v76, v152
	v_and_b32_e32 v76, 0xffff0000, v113
	v_sub_f32_e32 v81, v81, v171
	v_sub_f32_e32 v76, v76, v171
	v_fmac_f32_e32 v171, v77, v81
	v_lshlrev_b32_e32 v219, 16, v117
	v_lshlrev_b32_e32 v77, 16, v80
	s_waitcnt lgkmcnt(0)
	v_fmac_f32_e32 v171, v131, v76
	v_lshlrev_b32_e32 v76, 16, v111
	v_sub_f32_e32 v77, v77, v219
	v_sub_f32_e32 v76, v76, v219
	v_fmac_f32_e32 v219, v78, v77
	v_and_b32_e32 v117, 0xffff0000, v117
	v_and_b32_e32 v77, 0xffff0000, v80
	v_fmac_f32_e32 v219, v132, v76
	v_and_b32_e32 v76, 0xffff0000, v111
	v_sub_f32_e32 v77, v77, v117
	v_sub_f32_e32 v76, v76, v117
	v_fmac_f32_e32 v117, v79, v77
	v_add_u32_e32 v116, s68, v147
	v_fmac_f32_e32 v170, v130, v115
	v_fmac_f32_e32 v117, v133, v76
	ds_read_b128 v[130:133], v116
	v_add_u32_e32 v80, 0x25b00, v109
	v_add_u32_e32 v81, 0x25c00, v109
	ds_read_b128 v[152:155], v80
	ds_read_b128 v[76:79], v81
	s_waitcnt lgkmcnt(2)
; #define LAS __attribute__((address_space(3)))
; __device__ __forceinline__ unsigned cvtpk(float lo, float hi) { const f32x2 v = {lo, hi}; const bf16x2_t b = __builtin_convertvector(v, bf16x2_t); return __builtin_bit_cast(unsigned, b); }
; __device__ __forceinline__ float sigm(float x) { return __builtin_amdgcn_rcpf(1.0f + __expf(-x)); }
; #define MFMA16(a, b, c) __builtin_amdgcn_mfma_f32_16x16x32_bf16((a), (b), (c), 0, 0, 0)
; #define ZERO_ENDS2(A) do { if (!pz) A[1] = (u32x2){0u, 0u}; if (!nz) A[2] = (u32x2){0u, 0u}; } while (0)
; __device__ __forceinline__ void prep_y(int l, int b, int h, int dir, int c, LAS float* rg, const LAS float* cst, int lane) {
;     ...
;     ss += __shfl_xor(ss, 16); ss += __shfl_xor(ss, 32);
;     const float nrm = rsqrtf(ss + 1e-12f);
;     float cs = 0.f;
; #pragma unroll
;     for (int nb = 0; nb < 4; ++nb) {
;         f32x4 aI = {0.f, 0.f, 0.f, 0.f};
; #pragma unroll
;         for (int ks = 0; ks < 2; ++ks) aI = MFMA16(__builtin_bit_cast(bf16x8, wir[nb][ks]), bi[ks], aI);
;         const int co = nb * 16 + 4 * fq;
;         float rr[4];
;         ZERO_ENDS2(rr_[nb]);
;         mix4p(rr_[nb][0], rr_[nb][1], rr_[nb][2], cst + C_RMP + co, cst + C_RMN + co, rr);
;         const f32x4 ibias = *(const LAS f32x4*)(cst + C_IB + 64 * dir + co);
;         const f32x4 kkw = *(const LAS f32x4*)(cst + C_KK + co), kaw = *(const LAS f32x4*)(cst + C_KA + co), rkw = *(const LAS f32x4*)(cst + C_RK + co);
;         f32x4 va, vb, vkd, vr;
; #pragma unroll
;         for (int i = 0; i < 4; ++i) {
;             const float al = sigm(ibias[i] + aI[i]);
;             const float kraw = kk[4 * nb + i];
;             const float kn = kraw * kkw[i] * nrm;
;             const float kd = kraw * (1.0f + (al - 1.0f) * kaw[i]);
;             va[i] = -kn; vb[i] = kn * al; vkd[i] = kd; vr[i] = rr[i];
;             cs += rr[i] * kd * rkw[i];
;         }
;         *(LAS u32x4*)(rs_ + 128 + co) = (u32x4){cvtpk(0.25f * vb[0], 0.25f * vkd[0]), cvtpk(0.25f * vb[1], 0.25f * vkd[1]), cvtpk(0.25f * vb[2], 0.25f * vkd[2]), cvtpk(0.25f * vb[3], 0.25f * vkd[3])};
;         *(LAS u32x2*)(rs_ + 192 + (co >> 1)) = (u32x2){cvtpk(va[0], va[1]), cvtpk(va[2], va[3])};
;         *(LAS u32x2*)(rs_ + 224 + (co >> 1)) = (u32x2){cvtpk(vr[0], vr[1]), cvtpk(vr[2], vr[3])};
	v_add_f32_e32 v109, v148, v130
	v_mul_f32_e32 v109, 0xbfb8aa3b, v109
	v_exp_f32_e32 v109, v109
	v_mov_b32_e32 v224, v73
	s_waitcnt lgkmcnt(1)
	v_mov_b32_e32 v73, v152
	v_add_f32_e32 v109, 1.0, v109
	v_rcp_f32_e32 v130, v109
	v_add_f32_e32 v109, v149, v131
	v_mul_f32_e32 v109, 0xbfb8aa3b, v109
	v_exp_f32_e32 v109, v109
	v_add_f32_e32 v111, -1.0, v130
	v_mov_b32_e32 v225, v153
	v_pk_mul_f32 v[152:153], v[110:111], v[72:73]
	v_add_f32_e32 v109, 1.0, v109
	v_rcp_f32_e32 v148, v109
	v_add_f32_e32 v109, v150, v132
	v_mul_f32_e32 v109, 0xbfb8aa3b, v109
	v_exp_f32_e32 v109, v109
	v_add_f32_e32 v113, -1.0, v148
	v_mov_b32_e32 v156, v75
	v_mov_b32_e32 v75, v154
	v_add_f32_e32 v109, 1.0, v109
	v_rcp_f32_e32 v132, v109
	v_add_f32_e32 v109, v151, v133
	v_mul_f32_e32 v109, 0xbfb8aa3b, v109
	v_exp_f32_e32 v109, v109
	v_add_f32_e32 v115, -1.0, v132
	v_pk_mul_f32 v[226:227], v[112:113], v[224:225]
	v_mul_f32_e32 v131, v152, v152
	v_add_f32_e32 v109, 1.0, v109
	v_rcp_f32_e32 v150, v109
	v_mov_b32_e32 v157, v155
	v_pk_mul_f32 v[154:155], v[114:115], v[74:75]
	v_add_f32_e32 v109, -1.0, v150
	v_fmac_f32_e32 v131, v226, v226
	v_pk_mul_f32 v[158:159], v[108:109], v[156:157]
	v_fmac_f32_e32 v131, v154, v154
	v_fmac_f32_e32 v131, v158, v158
	v_fmac_f32_e32 v131, v107, v107
	v_pk_mul_f32 v[134:135], v[134:135], v[134:135]
	v_fmac_f32_e32 v131, v105, v105
	v_add_f32_e32 v105, v134, v131
	v_pk_mul_f32 v[136:137], v[94:95], v[136:137]
	v_add_f32_e32 v105, v135, v105
	v_pk_mul_f32 v[136:137], v[136:137], v[136:137]
	v_pk_fma_f32 v[72:73], v[110:111], v[72:73], s[2:3]
	v_pk_mul_f32 v[138:139], v[92:93], v[138:139]
	v_add_f32_e32 v105, v105, v136
	v_pk_mul_f32 v[138:139], v[138:139], v[138:139]
	v_add_f32_e32 v105, v137, v105
	v_pk_mul_f32 v[140:141], v[84:85], v[140:141]
	v_add_f32_e32 v105, v138, v105
	v_pk_mul_f32 v[140:141], v[140:141], v[140:141]
	v_add_f32_e32 v105, v139, v105
	v_pk_mul_f32 v[142:143], v[26:27], v[142:143]
	v_add_f32_e32 v105, v105, v140
	v_pk_mul_f32 v[142:143], v[142:143], v[142:143]
	v_add_f32_e32 v105, v141, v105
	v_add_f32_e32 v105, v142, v105
	v_add_f32_e32 v105, v143, v105
	v_mov_b32_e32 v107, v105
	v_mov_b32_e32 v131, v110
	v_mov_b32_e32 v149, v112
	v_pk_fma_f32 v[112:113], v[112:113], v[224:225], s[2:3]
	s_waitcnt lgkmcnt(0)
	v_permlane16_swap_b32_e32 v105, v107
	v_add_f32_e32 v105, v105, v107
	v_mov_b32_e32 v107, v105
	v_pk_fma_f32 v[74:75], v[114:115], v[74:75], s[2:3]
	v_mov_b32_e32 v133, v114
	v_mov_b32_e32 v151, v108
	s_waitcnt lgkmcnt(0)
	v_permlane32_swap_b32_e32 v105, v107
	v_add_f32_e32 v105, v105, v107
	v_add_f32_e32 v105, 0x2b8cbccc, v105
	v_cmp_gt_f32_e64 s[50:51], s19, v105
	v_mul_f32_e32 v107, 0x4b800000, v105
	v_mfma_f32_16x16x32_bf16 v[68:71], v[68:71], v[48:51], 0
	v_cndmask_b32_e64 v105, v105, v107, s[50:51]
	v_rsq_f32_e32 v105, v105
	v_cndmask_b32_e64 v14, v14, 0, vcc
	v_mfma_f32_16x16x32_bf16 v[64:67], v[64:67], v[52:55], v[68:71]
	v_cndmask_b32_e64 v20, 0, v20, s[48:49]
	v_mul_f32_e32 v107, 0x45800000, v105
	v_cndmask_b32_e64 v168, v105, v107, s[50:51]
	v_pk_mul_f32 v[134:135], v[152:153], v[168:169]
	v_mfma_f32_16x16x32_bf16 v[60:63], v[60:63], v[48:51], 0
	v_mov_b32_e32 v135, v73
	v_pk_mul_f32 v[110:111], v[130:131], v[134:135]
	v_pk_mul_f32 v[130:131], v[226:227], v[168:169]
	v_mul_f32_e32 v72, v170, v111
	v_mov_b32_e32 v131, v113
	v_pk_mul_f32 v[112:113], v[148:149], v[130:131]
	v_fma_f32 v72, v76, v72, 0
	v_mul_f32_e32 v73, v171, v113
	v_fmac_f32_e32 v72, v77, v73
	v_pk_mul_f32 v[76:77], v[154:155], v[168:169]
	v_xor_b32_e32 v105, 0x80000000, v130
	v_mov_b32_e32 v77, v75
	v_pk_mul_f32 v[114:115], v[132:133], v[76:77]
	v_pk_add_f32 v[130:131], v[76:77], 0 neg_lo:[1,1] neg_hi:[1,1]
	v_pk_mul_f32 v[74:75], v[158:159], v[168:169]
	v_pk_fma_f32 v[76:77], v[108:109], v[156:157], s[2:3]
	v_mul_f32_e32 v73, v219, v115
	v_mov_b32_e32 v75, v77
	v_pk_mul_f32 v[108:109], v[150:151], v[74:75]
	v_fmac_f32_e32 v72, v78, v73
	v_xor_b32_e32 v107, 0x80000000, v74
	v_mul_f32_e32 v73, v117, v109
	v_pk_mul_f32 v[74:75], v[110:111], s[20:21] op_sel_hi:[1,0]
	v_pk_mul_f32 v[76:77], v[112:113], s[20:21] op_sel_hi:[1,0]
	v_fmac_f32_e32 v72, v79, v73
	v_cvt_pk_bf16_f32 v74, v74, v75
	v_cvt_pk_bf16_f32 v75, v76, v77
	v_pk_mul_f32 v[76:77], v[114:115], s[20:21] op_sel_hi:[1,0]
	v_pk_mul_f32 v[78:79], v[108:109], s[20:21] op_sel_hi:[1,0]
	v_add_u32_e32 v73, v33, v147
	v_pk_add_f32 v[132:133], v[134:135], 0 neg_lo:[1,1] neg_hi:[1,1]
	v_cvt_pk_bf16_f32 v76, v76, v77
	v_cvt_pk_bf16_f32 v77, v78, v79
	v_sub_u32_e32 v78, v73, v32
	ds_write_b128 v73, v[74:77] offset:33280
	v_cvt_pk_bf16_f32 v74, v132, v105
	v_cvt_pk_bf16_f32 v75, v130, v107
	v_cvt_pk_bf16_f32 v76, v170, v171
	v_cvt_pk_bf16_f32 v77, v219, v117
	v_add_u32_e32 v78, 0x8000, v78
	ds_write2_b64 v78, v[74:75], v[76:77] offset0:96 offset1:112
	ds_read_b128 v[68:71], v82 offset:64
	ds_read_b128 v[74:77], v83 offset:64
	v_cndmask_b32_e64 v79, v98, 0, vcc
	v_cndmask_b32_e64 v78, v99, 0, vcc
	v_cndmask_b32_e64 v98, 0, v101, s[48:49]
	v_cndmask_b32_e64 v99, 0, v100, s[48:49]
	v_lshlrev_b32_e32 v117, 16, v96
	v_lshlrev_b32_e32 v101, 16, v79
	v_lshlrev_b32_e32 v100, 16, v99
	v_sub_f32_e32 v101, v101, v117
	v_sub_f32_e32 v100, v100, v117
	s_waitcnt lgkmcnt(1)
	v_fmac_f32_e32 v117, v68, v101
	s_waitcnt lgkmcnt(0)
; #define LAS __attribute__((address_space(3)))
; __device__ __forceinline__ unsigned cvtpk(float lo, float hi) { const f32x2 v = {lo, hi}; const bf16x2_t b = __builtin_convertvector(v, bf16x2_t); return __builtin_bit_cast(unsigned, b); }
; __device__ __forceinline__ float sigm(float x) { return __builtin_amdgcn_rcpf(1.0f + __expf(-x)); }
; #define MFMA16(a, b, c) __builtin_amdgcn_mfma_f32_16x16x32_bf16((a), (b), (c), 0, 0, 0)
; #define ZERO_ENDS2(A) do { if (!pz) A[1] = (u32x2){0u, 0u}; if (!nz) A[2] = (u32x2){0u, 0u}; } while (0)
; __device__ __forceinline__ void prep_y(int l, int b, int h, int dir, int c, LAS float* rg, const LAS float* cst, int lane) {
;     ...
;     for (int nb = 0; nb < 4; ++nb) {
;         f32x4 aI = {0.f, 0.f, 0.f, 0.f};
; #pragma unroll
;         for (int ks = 0; ks < 2; ++ks) aI = MFMA16(__builtin_bit_cast(bf16x8, wir[nb][ks]), bi[ks], aI);
;         const int co = nb * 16 + 4 * fq;
;         float rr[4];
;         ZERO_ENDS2(rr_[nb]);
;         mix4p(rr_[nb][0], rr_[nb][1], rr_[nb][2], cst + C_RMP + co, cst + C_RMN + co, rr);
;         const f32x4 ibias = *(const LAS f32x4*)(cst + C_IB + 64 * dir + co);
;         const f32x4 kkw = *(const LAS f32x4*)(cst + C_KK + co), kaw = *(const LAS f32x4*)(cst + C_KA + co), rkw = *(const LAS f32x4*)(cst + C_RK + co);
;         f32x4 va, vb, vkd, vr;
; #pragma unroll
;         for (int i = 0; i < 4; ++i) {
;             const float al = sigm(ibias[i] + aI[i]);
;             const float kraw = kk[4 * nb + i];
;             const float kn = kraw * kkw[i] * nrm;
;             const float kd = kraw * (1.0f + (al - 1.0f) * kaw[i]);
;             va[i] = -kn; vb[i] = kn * al; vkd[i] = kd; vr[i] = rr[i];
;             cs += rr[i] * kd * rkw[i];
;         }
;         *(LAS u32x4*)(rs_ + 128 + co) = (u32x4){cvtpk(0.25f * vb[0], 0.25f * vkd[0]), cvtpk(0.25f * vb[1], 0.25f * vkd[1]), cvtpk(0.25f * vb[2], 0.25f * vkd[2]), cvtpk(0.25f * vb[3], 0.25f * vkd[3])};
;         *(LAS u32x2*)(rs_ + 192 + (co >> 1)) = (u32x2){cvtpk(va[0], va[1]), cvtpk(va[2], va[3])};
;         *(LAS u32x2*)(rs_ + 224 + (co >> 1)) = (u32x2){cvtpk(vr[0], vr[1]), cvtpk(vr[2], vr[3])};
	v_fmac_f32_e32 v117, v74, v100
	v_and_b32_e32 v130, 0xffff0000, v96
	v_and_b32_e32 v74, 0xffff0000, v79
	v_and_b32_e32 v68, 0xffff0000, v99
	v_sub_f32_e32 v74, v74, v130
	v_sub_f32_e32 v68, v68, v130
	v_fmac_f32_e32 v130, v69, v74
	v_lshlrev_b32_e32 v131, 16, v97
	v_lshlrev_b32_e32 v69, 16, v78
	v_fmac_f32_e32 v130, v75, v68
	v_lshlrev_b32_e32 v68, 16, v98
	v_sub_f32_e32 v69, v69, v131
	v_sub_f32_e32 v68, v68, v131
	v_fmac_f32_e32 v131, v70, v69
	v_and_b32_e32 v132, 0xffff0000, v97
	v_and_b32_e32 v69, 0xffff0000, v78
	v_fmac_f32_e32 v131, v76, v68
	v_and_b32_e32 v68, 0xffff0000, v98
	s_nop 0
	v_pk_add_f32 v[68:69], v[68:69], v[132:133] op_sel_hi:[1,0] neg_lo:[0,1] neg_hi:[0,1]
	v_fmac_f32_e32 v132, v71, v69
	v_fmac_f32_e32 v132, v77, v68
	ds_read_b128 v[74:77], v116 offset:64
	ds_read_b128 v[96:99], v2 offset:64
	ds_read_b128 v[108:111], v80 offset:64
	ds_read_b128 v[68:71], v81 offset:64
	s_waitcnt lgkmcnt(3)
	v_add_f32_e32 v65, v65, v75
	v_mul_f32_e32 v65, 0xbfb8aa3b, v65
	v_exp_f32_e32 v65, v65
	v_add_f32_e32 v64, v64, v74
	v_mul_f32_e32 v64, 0xbfb8aa3b, v64
	v_exp_f32_e32 v64, v64
	v_add_f32_e32 v65, 1.0, v65
	v_rcp_f32_e32 v74, v65
	v_add_f32_e32 v65, v66, v76
	v_mul_f32_e32 v65, 0xbfb8aa3b, v65
	v_exp_f32_e32 v65, v65
	v_add_f32_e32 v64, 1.0, v64
	v_rcp_f32_e32 v64, v64
	v_add_f32_e32 v105, -1.0, v74
	v_add_f32_e32 v65, 1.0, v65
	v_rcp_f32_e32 v66, v65
	v_add_f32_e32 v65, v67, v77
	v_mul_f32_e32 v65, 0xbfb8aa3b, v65
	v_exp_f32_e32 v65, v65
	v_add_f32_e32 v107, -1.0, v64
	s_waitcnt lgkmcnt(2)
	v_mov_b32_e32 v112, v96
	s_waitcnt lgkmcnt(1)
	v_mov_b32_e32 v113, v108
	v_pk_mul_f32 v[114:115], v[106:107], v[96:97]
	v_mov_b32_e32 v108, v97
	v_add_f32_e32 v65, 1.0, v65
	v_pk_mul_f32 v[114:115], v[168:169], v[114:115]
	v_pk_fma_f32 v[112:113], v[106:107], v[112:113], s[2:3]
	v_pk_mul_f32 v[96:97], v[104:105], v[108:109]
	v_rcp_f32_e32 v76, v65
	v_mov_b32_e32 v115, v113
	v_mov_b32_e32 v65, v106
	v_pk_mul_f32 v[96:97], v[168:169], v[96:97]
	v_pk_fma_f32 v[106:107], v[104:105], v[108:109], s[2:3]
	v_pk_mul_f32 v[64:65], v[114:115], v[64:65]
	v_mov_b32_e32 v97, v107
	v_mov_b32_e32 v75, v104
	v_mul_f32_e32 v67, v117, v65
	v_pk_mul_f32 v[64:65], v[64:65], s[20:21] op_sel_hi:[1,0]
	v_pk_mul_f32 v[74:75], v[96:97], v[74:75]
	s_waitcnt lgkmcnt(0)
	v_fmac_f32_e32 v72, v68, v67
	v_cvt_pk_bf16_f32 v64, v64, v65
	v_mul_f32_e32 v65, v130, v75
	v_fmac_f32_e32 v72, v69, v65
	v_pk_mul_f32 v[68:69], v[74:75], s[20:21] op_sel_hi:[1,0]
	v_add_f32_e32 v79, -1.0, v66
	v_cvt_pk_bf16_f32 v65, v68, v69
	v_mov_b32_e32 v78, v102
	v_mov_b32_e32 v68, v98
	v_mov_b32_e32 v69, v110
	v_pk_mul_f32 v[74:75], v[102:103], v[98:99]
	v_pk_fma_f32 v[68:69], v[78:79], v[68:69], s[2:3]
	v_pk_mul_f32 v[74:75], v[168:169], v[74:75]
	v_add_f32_e32 v101, -1.0, v76
	v_mov_b32_e32 v75, v69
	v_mov_b32_e32 v67, v102
	v_mov_b32_e32 v100, v103
	v_mov_b32_e32 v110, v99
	v_pk_add_f32 v[68:69], v[74:75], 0 neg_lo:[1,1] neg_hi:[1,1]
	v_pk_mul_f32 v[66:67], v[74:75], v[66:67]
	v_pk_mul_f32 v[74:75], v[100:101], v[110:111]
	v_pk_fma_f32 v[78:79], v[100:101], v[110:111], s[2:3]
	v_pk_mul_f32 v[74:75], v[168:169], v[74:75]
	v_mov_b32_e32 v77, v103
	v_mul_f32_e32 v69, v131, v67
	v_mov_b32_e32 v75, v79
	v_fmac_f32_e32 v72, v70, v69
	v_pk_mul_f32 v[66:67], v[66:67], s[20:21] op_sel_hi:[1,0]
	v_xor_b32_e32 v69, 0x80000000, v74
	v_pk_mul_f32 v[74:75], v[74:75], v[76:77]
	v_cvt_pk_bf16_f32 v66, v66, v67
	v_mul_f32_e32 v67, v132, v75
	v_fmac_f32_e32 v72, v71, v67
	v_pk_mul_f32 v[70:71], v[74:75], s[20:21] op_sel_hi:[1,0]
	v_pk_add_f32 v[112:113], v[114:115], 0 neg_lo:[1,1] neg_hi:[1,1]
	v_xor_b32_e32 v105, 0x80000000, v96
	v_cvt_pk_bf16_f32 v67, v70, v71
	ds_write_b128 v73, v[64:67] offset:33344
	v_cvt_pk_bf16_f32 v64, v112, v105
	v_cvt_pk_bf16_f32 v65, v68, v69
	v_add_u32_e32 v32, v32, v33
	ds_write_b64 v32, v[64:65] offset:33568
	v_cvt_pk_bf16_f32 v64, v117, v130
	v_cvt_pk_bf16_f32 v65, v131, v132
	ds_write_b64 v32, v[64:65] offset:33696
	v_mfma_f32_16x16x32_bf16 v[56:59], v[56:59], v[52:55], v[60:63]
	s_nop 2
	ds_read_b128 v[60:63], v82 offset:128
	ds_read_b128 v[64:67], v83 offset:128
	v_cndmask_b32_e64 v68, v88, 0, vcc
	v_cndmask_b32_e64 v70, 0, v90, s[48:49]
	v_lshlrev_b32_e32 v100, 16, v86
	v_lshlrev_b32_e32 v74, 16, v68
	v_lshlrev_b32_e32 v71, 16, v70
	v_sub_f32_e32 v74, v74, v100
	v_sub_f32_e32 v71, v71, v100
	s_waitcnt lgkmcnt(1)
	v_fmac_f32_e32 v100, v60, v74
	s_waitcnt lgkmcnt(0)
	v_fmac_f32_e32 v100, v64, v71
	v_and_b32_e32 v101, 0xffff0000, v86
	v_and_b32_e32 v64, 0xffff0000, v68
	v_cndmask_b32_e64 v33, v89, 0, vcc
	v_and_b32_e32 v60, 0xffff0000, v70
	v_sub_f32_e32 v64, v64, v101
	v_cndmask_b32_e64 v69, 0, v91, s[48:49]
	v_sub_f32_e32 v60, v60, v101
	v_fmac_f32_e32 v101, v61, v64
	v_lshlrev_b32_e32 v102, 16, v87
	v_lshlrev_b32_e32 v61, 16, v33
	v_fmac_f32_e32 v101, v65, v60
	v_lshlrev_b32_e32 v60, 16, v69
	s_nop 0
	v_pk_add_f32 v[60:61], v[60:61], v[102:103] op_sel_hi:[1,0] neg_lo:[0,1] neg_hi:[0,1]
	v_fmac_f32_e32 v102, v62, v61
	v_and_b32_e32 v103, 0xffff0000, v87
	v_and_b32_e32 v33, 0xffff0000, v33
	v_fmac_f32_e32 v102, v66, v60
	v_and_b32_e32 v60, 0xffff0000, v69
	v_sub_f32_e32 v33, v33, v103
	v_sub_f32_e32 v60, v60, v103
	v_fmac_f32_e32 v103, v63, v33
	v_fmac_f32_e32 v103, v67, v60
	ds_read_b128 v[64:67], v116 offset:128
	ds_read_b128 v[68:71], v2 offset:128
	ds_read_b128 v[74:77], v80 offset:128
	ds_read_b128 v[60:63], v81 offset:128
	v_mov_b32_e32 v78, v94
	s_waitcnt lgkmcnt(3)
	v_add_f32_e32 v33, v56, v64
	v_mul_f32_e32 v33, 0xbfb8aa3b, v33
	v_exp_f32_e32 v33, v33
	s_waitcnt lgkmcnt(2)
	v_mov_b32_e32 v96, v68
	s_waitcnt lgkmcnt(1)
; #define LAS __attribute__((address_space(3)))
; __device__ __forceinline__ unsigned cvtpk(float lo, float hi) { const f32x2 v = {lo, hi}; const bf16x2_t b = __builtin_convertvector(v, bf16x2_t); return __builtin_bit_cast(unsigned, b); }
; __device__ __forceinline__ float sigm(float x) { return __builtin_amdgcn_rcpf(1.0f + __expf(-x)); }
; #define MFMA16(a, b, c) __builtin_amdgcn_mfma_f32_16x16x32_bf16((a), (b), (c), 0, 0, 0)
; #define ZERO_ENDS2(A) do { if (!pz) A[1] = (u32x2){0u, 0u}; if (!nz) A[2] = (u32x2){0u, 0u}; } while (0)
; __device__ __forceinline__ void prep_y(int l, int b, int h, int dir, int c, LAS float* rg, const LAS float* cst, int lane) {
;     ...
;     for (int nb = 0; nb < 4; ++nb) {
;         f32x4 aI = {0.f, 0.f, 0.f, 0.f};
; #pragma unroll
;         for (int ks = 0; ks < 2; ++ks) aI = MFMA16(__builtin_bit_cast(bf16x8, wir[nb][ks]), bi[ks], aI);
;         const int co = nb * 16 + 4 * fq;
;         float rr[4];
;         ZERO_ENDS2(rr_[nb]);
;         mix4p(rr_[nb][0], rr_[nb][1], rr_[nb][2], cst + C_RMP + co, cst + C_RMN + co, rr);
;         const f32x4 ibias = *(const LAS f32x4*)(cst + C_IB + 64 * dir + co);
;         const f32x4 kkw = *(const LAS f32x4*)(cst + C_KK + co), kaw = *(const LAS f32x4*)(cst + C_KA + co), rkw = *(const LAS f32x4*)(cst + C_RK + co);
;         f32x4 va, vb, vkd, vr;
; #pragma unroll
;         for (int i = 0; i < 4; ++i) {
;             const float al = sigm(ibias[i] + aI[i]);
;             const float kraw = kk[4 * nb + i];
;             const float kn = kraw * kkw[i] * nrm;
;             const float kd = kraw * (1.0f + (al - 1.0f) * kaw[i]);
;             va[i] = -kn; vb[i] = kn * al; vkd[i] = kd; vr[i] = rr[i];
;             cs += rr[i] * kd * rkw[i];
;         }
;         *(LAS u32x4*)(rs_ + 128 + co) = (u32x4){cvtpk(0.25f * vb[0], 0.25f * vkd[0]), cvtpk(0.25f * vb[1], 0.25f * vkd[1]), cvtpk(0.25f * vb[2], 0.25f * vkd[2]), cvtpk(0.25f * vb[3], 0.25f * vkd[3])};
;         *(LAS u32x2*)(rs_ + 192 + (co >> 1)) = (u32x2){cvtpk(va[0], va[1]), cvtpk(va[2], va[3])};
;         *(LAS u32x2*)(rs_ + 224 + (co >> 1)) = (u32x2){cvtpk(vr[0], vr[1]), cvtpk(vr[2], vr[3])};
	v_mov_b32_e32 v97, v74
	v_pk_mul_f32 v[98:99], v[94:95], v[68:69]
	v_add_f32_e32 v33, 1.0, v33
	v_rcp_f32_e32 v56, v33
	v_add_f32_e32 v33, v57, v65
	v_mul_f32_e32 v33, 0xbfb8aa3b, v33
	v_exp_f32_e32 v33, v33
	v_add_f32_e32 v79, -1.0, v56
	v_mov_b32_e32 v86, v95
	v_mov_b32_e32 v74, v69
	v_add_f32_e32 v33, 1.0, v33
	v_rcp_f32_e32 v64, v33
	v_add_f32_e32 v33, v58, v66
	v_mul_f32_e32 v33, 0xbfb8aa3b, v33
	v_exp_f32_e32 v33, v33
	v_add_f32_e32 v87, -1.0, v64
	v_pk_mul_f32 v[98:99], v[168:169], v[98:99]
	v_pk_fma_f32 v[78:79], v[78:79], v[96:97], s[2:3]
	v_add_f32_e32 v33, 1.0, v33
	v_rcp_f32_e32 v58, v33
	v_add_f32_e32 v33, v59, v67
	v_mul_f32_e32 v33, 0xbfb8aa3b, v33
	v_exp_f32_e32 v33, v33
	v_pk_mul_f32 v[68:69], v[86:87], v[74:75]
	v_mov_b32_e32 v99, v79
	v_mov_b32_e32 v57, v94
	v_pk_mul_f32 v[68:69], v[168:169], v[68:69]
	v_pk_fma_f32 v[74:75], v[86:87], v[74:75], s[2:3]
	v_add_f32_e32 v33, 1.0, v33
	v_pk_mul_f32 v[56:57], v[98:99], v[56:57]
	v_mov_b32_e32 v69, v75
	v_mov_b32_e32 v65, v95
	v_rcp_f32_e32 v66, v33
	v_mul_f32_e32 v33, v100, v57
	v_pk_mul_f32 v[56:57], v[56:57], s[20:21] op_sel_hi:[1,0]
	v_pk_mul_f32 v[64:65], v[68:69], v[64:65]
	s_waitcnt lgkmcnt(0)
	v_fmac_f32_e32 v72, v60, v33
	v_cvt_pk_bf16_f32 v56, v56, v57
	v_mul_f32_e32 v57, v101, v65
	v_fmac_f32_e32 v72, v61, v57
	v_pk_mul_f32 v[60:61], v[64:65], s[20:21] op_sel_hi:[1,0]
	v_add_f32_e32 v89, -1.0, v58
	v_cvt_pk_bf16_f32 v57, v60, v61
	v_mov_b32_e32 v88, v92
	v_mov_b32_e32 v60, v70
	v_mov_b32_e32 v61, v76
	v_pk_mul_f32 v[64:65], v[92:93], v[70:71]
	v_pk_fma_f32 v[60:61], v[88:89], v[60:61], s[2:3]
	v_pk_mul_f32 v[64:65], v[168:169], v[64:65]
	v_add_f32_e32 v91, -1.0, v66
	v_mov_b32_e32 v65, v61
	v_mov_b32_e32 v59, v92
	v_mov_b32_e32 v90, v93
	v_mov_b32_e32 v76, v71
	v_pk_add_f32 v[60:61], v[64:65], 0 neg_lo:[1,1] neg_hi:[1,1]
	v_pk_mul_f32 v[58:59], v[64:65], v[58:59]
	v_pk_mul_f32 v[64:65], v[90:91], v[76:77]
	v_xor_b32_e32 v33, 0x80000000, v68
	v_pk_mul_f32 v[64:65], v[168:169], v[64:65]
	v_pk_fma_f32 v[68:69], v[90:91], v[76:77], s[2:3]
	v_mov_b32_e32 v67, v93
	v_mul_f32_e32 v61, v102, v59
	v_mov_b32_e32 v65, v69
	v_fmac_f32_e32 v72, v62, v61
	v_pk_mul_f32 v[58:59], v[58:59], s[20:21] op_sel_hi:[1,0]
	v_xor_b32_e32 v61, 0x80000000, v64
	v_pk_mul_f32 v[64:65], v[64:65], v[66:67]
	v_cvt_pk_bf16_f32 v58, v58, v59
	v_mul_f32_e32 v59, v103, v65
	v_fmac_f32_e32 v72, v63, v59
	v_pk_mul_f32 v[62:63], v[64:65], s[20:21] op_sel_hi:[1,0]
	v_pk_add_f32 v[78:79], v[98:99], 0 neg_lo:[1,1] neg_hi:[1,1]
	v_cvt_pk_bf16_f32 v59, v62, v63
	v_mfma_f32_16x16x32_bf16 v[44:47], v[44:47], v[48:51], 0
	ds_write_b128 v73, v[56:59] offset:33408
	v_cvt_pk_bf16_f32 v56, v78, v33
	v_cvt_pk_bf16_f32 v57, v60, v61
	ds_write_b64 v32, v[56:57] offset:33600
	v_cvt_pk_bf16_f32 v56, v100, v101
	v_cvt_pk_bf16_f32 v57, v102, v103
	ds_write_b64 v32, v[56:57] offset:33728
	v_mfma_f32_16x16x32_bf16 v[40:43], v[40:43], v[52:55], v[44:47]
	s_nop 2
	ds_read_b128 v[44:47], v82 offset:192
	ds_read_b128 v[48:51], v83 offset:192
	v_lshlrev_b32_e32 v53, 16, v14
	v_and_b32_e32 v66, 0xffff0000, v10
	v_and_b32_e32 v14, 0xffff0000, v14
	v_cndmask_b32_e64 v15, v15, 0, vcc
	v_lshlrev_b32_e32 v33, 16, v10
	v_and_b32_e32 v10, 0xffff0000, v20
	v_sub_f32_e32 v14, v14, v66
	v_cndmask_b32_e64 v21, 0, v21, s[48:49]
	v_sub_f32_e32 v10, v10, v66
	s_waitcnt lgkmcnt(1)
	v_fmac_f32_e32 v66, v45, v14
	v_lshlrev_b32_e32 v67, 16, v11
	v_lshlrev_b32_e32 v14, 16, v15
	s_waitcnt lgkmcnt(0)
	v_fmac_f32_e32 v66, v49, v10
	v_lshlrev_b32_e32 v10, 16, v21
	v_sub_f32_e32 v14, v14, v67
	v_sub_f32_e32 v10, v10, v67
	v_fmac_f32_e32 v67, v46, v14
	v_and_b32_e32 v68, 0xffff0000, v11
	v_and_b32_e32 v11, 0xffff0000, v15
	v_lshlrev_b32_e32 v52, 16, v20
	v_sub_f32_e32 v53, v53, v33
	v_fmac_f32_e32 v67, v50, v10
	v_and_b32_e32 v10, 0xffff0000, v21
	s_nop 0
	v_sub_f32_e32 v52, v52, v33
	v_fmac_f32_e32 v33, v44, v53
	v_pk_add_f32 v[10:11], v[10:11], v[68:69] op_sel_hi:[1,0] neg_lo:[0,1] neg_hi:[0,1]
	v_fmac_f32_e32 v68, v47, v11
	v_fmac_f32_e32 v33, v48, v52
	v_fmac_f32_e32 v68, v51, v10
	ds_read_b128 v[48:51], v116 offset:192
	ds_read_b128 v[52:55], v2 offset:192
	ds_read_b128 v[56:59], v80 offset:192
	ds_read_b128 v[44:47], v81 offset:192
	v_mov_b32_e32 v14, v84
	s_waitcnt lgkmcnt(3)
; #define LAS __attribute__((address_space(3)))
; __device__ __forceinline__ unsigned cvtpk(float lo, float hi) { const f32x2 v = {lo, hi}; const bf16x2_t b = __builtin_convertvector(v, bf16x2_t); return __builtin_bit_cast(unsigned, b); }
; __device__ __forceinline__ float sigm(float x) { return __builtin_amdgcn_rcpf(1.0f + __expf(-x)); }
; #define MFMA16(a, b, c) __builtin_amdgcn_mfma_f32_16x16x32_bf16((a), (b), (c), 0, 0, 0)
; #define ZERO_ENDS2(A) do { if (!pz) A[1] = (u32x2){0u, 0u}; if (!nz) A[2] = (u32x2){0u, 0u}; } while (0)
; __device__ __forceinline__ void prep_y(int l, int b, int h, int dir, int c, LAS float* rg, const LAS float* cst, int lane) {
;     ...
;     for (int nb = 0; nb < 4; ++nb) {
;         f32x4 aI = {0.f, 0.f, 0.f, 0.f};
; #pragma unroll
;         for (int ks = 0; ks < 2; ++ks) aI = MFMA16(__builtin_bit_cast(bf16x8, wir[nb][ks]), bi[ks], aI);
;         const int co = nb * 16 + 4 * fq;
;         float rr[4];
;         ZERO_ENDS2(rr_[nb]);
;         mix4p(rr_[nb][0], rr_[nb][1], rr_[nb][2], cst + C_RMP + co, cst + C_RMN + co, rr);
;         const f32x4 ibias = *(const LAS f32x4*)(cst + C_IB + 64 * dir + co);
;         const f32x4 kkw = *(const LAS f32x4*)(cst + C_KK + co), kaw = *(const LAS f32x4*)(cst + C_KA + co), rkw = *(const LAS f32x4*)(cst + C_RK + co);
;         f32x4 va, vb, vkd, vr;
; #pragma unroll
;         for (int i = 0; i < 4; ++i) {
;             const float al = sigm(ibias[i] + aI[i]);
;             const float kraw = kk[4 * nb + i];
;             const float kn = kraw * kkw[i] * nrm;
;             const float kd = kraw * (1.0f + (al - 1.0f) * kaw[i]);
;             va[i] = -kn; vb[i] = kn * al; vkd[i] = kd; vr[i] = rr[i];
;             cs += rr[i] * kd * rkw[i];
;         }
;         *(LAS u32x4*)(rs_ + 128 + co) = (u32x4){cvtpk(0.25f * vb[0], 0.25f * vkd[0]), cvtpk(0.25f * vb[1], 0.25f * vkd[1]), cvtpk(0.25f * vb[2], 0.25f * vkd[2]), cvtpk(0.25f * vb[3], 0.25f * vkd[3])};
;         *(LAS u32x2*)(rs_ + 192 + (co >> 1)) = (u32x2){cvtpk(va[0], va[1]), cvtpk(va[2], va[3])};
;         *(LAS u32x2*)(rs_ + 224 + (co >> 1)) = (u32x2){cvtpk(vr[0], vr[1]), cvtpk(vr[2], vr[3])};
;     }
;     cs += __shfl_xor(cs, 16); cs += __shfl_xor(cs, 32);
;     if (fq == 0) ((float*)(ws + OFF_COEF))[((size_t)dir * T + row) * 16 + h] = cs;
	v_add_f32_e32 v2, v40, v48
	v_mul_f32_e32 v2, 0xbfb8aa3b, v2
	v_exp_f32_e32 v2, v2
	s_waitcnt lgkmcnt(2)
	v_mov_b32_e32 v40, v52
	v_pk_mul_f32 v[64:65], v[84:85], v[52:53]
	v_mov_b32_e32 v11, v84
	v_add_f32_e32 v2, 1.0, v2
	v_rcp_f32_e32 v10, v2
	v_add_f32_e32 v2, v41, v49
	v_mul_f32_e32 v2, 0xbfb8aa3b, v2
	v_exp_f32_e32 v2, v2
	v_add_f32_e32 v15, -1.0, v10
	s_waitcnt lgkmcnt(1)
	v_mov_b32_e32 v41, v56
	v_pk_mul_f32 v[64:65], v[168:169], v[64:65]
	v_add_f32_e32 v2, 1.0, v2
	v_rcp_f32_e32 v20, v2
	v_add_f32_e32 v2, v42, v50
	v_mul_f32_e32 v2, 0xbfb8aa3b, v2
	v_exp_f32_e32 v2, v2
	v_pk_fma_f32 v[14:15], v[14:15], v[40:41], s[2:3]
	v_add_f32_e32 v49, -1.0, v20
	v_add_f32_e32 v2, 1.0, v2
	v_rcp_f32_e32 v42, v2
	v_add_f32_e32 v2, v43, v51
	v_mul_f32_e32 v2, 0xbfb8aa3b, v2
	v_exp_f32_e32 v2, v2
	v_mov_b32_e32 v65, v15
	v_pk_mul_f32 v[10:11], v[64:65], v[10:11]
	v_mov_b32_e32 v48, v85
	v_add_f32_e32 v2, 1.0, v2
	v_rcp_f32_e32 v50, v2
	v_mul_f32_e32 v2, v33, v11
	v_pk_mul_f32 v[10:11], v[10:11], s[20:21] op_sel_hi:[1,0]
	v_mov_b32_e32 v56, v53
	v_cvt_pk_bf16_f32 v40, v10, v11
	v_pk_mul_f32 v[10:11], v[48:49], v[56:57]
	v_pk_fma_f32 v[48:49], v[48:49], v[56:57], s[2:3]
	v_pk_mul_f32 v[10:11], v[168:169], v[10:11]
	v_mov_b32_e32 v21, v85
	v_mov_b32_e32 v11, v49
	v_pk_add_f32 v[14:15], v[64:65], 0 neg_lo:[1,1] neg_hi:[1,1]
	s_waitcnt lgkmcnt(0)
	v_fmac_f32_e32 v72, v44, v2
	v_xor_b32_e32 v2, 0x80000000, v10
	v_pk_mul_f32 v[10:11], v[10:11], v[20:21]
	v_add_f32_e32 v61, -1.0, v42
	v_mul_f32_e32 v15, v66, v11
	v_pk_mul_f32 v[10:11], v[10:11], s[20:21] op_sel_hi:[1,0]
	v_mov_b32_e32 v60, v26
	v_cvt_pk_bf16_f32 v41, v10, v11
	v_mov_b32_e32 v10, v54
	v_mov_b32_e32 v11, v58
	v_pk_mul_f32 v[20:21], v[26:27], v[54:55]
	v_pk_fma_f32 v[10:11], v[60:61], v[10:11], s[2:3]
	v_pk_mul_f32 v[20:21], v[168:169], v[20:21]
	v_mov_b32_e32 v43, v26
	v_mov_b32_e32 v21, v11
	v_pk_add_f32 v[10:11], v[20:21], 0 neg_lo:[1,1] neg_hi:[1,1]
	v_pk_mul_f32 v[20:21], v[20:21], v[42:43]
	v_add_f32_e32 v63, -1.0, v50
	v_mul_f32_e32 v11, v67, v21
	v_pk_mul_f32 v[20:21], v[20:21], s[20:21] op_sel_hi:[1,0]
	v_mov_b32_e32 v62, v27
	v_mov_b32_e32 v58, v55
	v_cvt_pk_bf16_f32 v42, v20, v21
	v_pk_mul_f32 v[20:21], v[62:63], v[58:59]
	v_fmac_f32_e32 v72, v45, v15
	v_pk_mul_f32 v[20:21], v[168:169], v[20:21]
	v_pk_fma_f32 v[44:45], v[62:63], v[58:59], s[2:3]
	v_mov_b32_e32 v51, v27
	v_mov_b32_e32 v21, v45
	v_fmac_f32_e32 v72, v46, v11
	v_xor_b32_e32 v11, 0x80000000, v20
	v_pk_mul_f32 v[20:21], v[20:21], v[50:51]
	v_cvt_pk_bf16_f32 v14, v14, v2
	v_mul_f32_e32 v15, v68, v21
	v_fmac_f32_e32 v72, v47, v15
	v_mov_b32_e32 v196, v72
	v_pk_mul_f32 v[20:21], v[20:21], s[20:21] op_sel_hi:[1,0]
	v_cvt_pk_bf16_f32 v15, v10, v11
	v_cvt_pk_bf16_f32 v43, v20, v21
	v_cvt_pk_bf16_f32 v10, v33, v66
	v_cvt_pk_bf16_f32 v11, v67, v68
	s_waitcnt lgkmcnt(0)
	v_permlane16_swap_b32_e32 v72, v196
	v_add_f32_e32 v2, v196, v72
	ds_write_b128 v73, v[40:43] offset:33472
	ds_write_b64 v32, v[10:11] offset:33760
	v_mov_b32_e32 v196, v2
	s_nop 1
	v_permlane32_swap_b32_e32 v2, v196
	v_cmp_gt_u32_e32 vcc, 16, v144
	ds_write_b64 v32, v[14:15] offset:33632
	s_and_saveexec_b64 s[6:7], vcc
	s_cbranch_execz .LBB0_374
	v_readlane_b32 s35, v255, 56
	s_add_u32 s48, s52, s35
	s_addc_u32 s49, s53, 0
	v_lshlrev_b64 v[4:5], 6, v[4:5]
	v_lshl_add_u64 v[4:5], s[48:49], 0, v[4:5]
	s_mov_b32 s91, s97
	v_lshl_add_u64 v[4:5], v[4:5], 0, s[90:91]
	v_add_co_u32_e32 v4, vcc, 0xdd00000, v4
	s_waitcnt lgkmcnt(1)
	v_add_f32_e32 v2, v2, v196
	v_addc_co_u32_e32 v5, vcc, 0, v5, vcc
	global_store_dword v[4:5], v2, off

; #define LAS __attribute__((address_space(3)))
; __device__ __forceinline__ bf16x8 pack8(const float* f) { return __builtin_bit_cast(bf16x8, pack8u(f)); }
; #define ZERO_ENDS4(A) do { if (!pz) A[1] = (u32x4){0u, 0u, 0u, 0u}; if (!nz) A[2] = (u32x4){0u, 0u, 0u, 0u}; } while (0)
; __device__ __forceinline__ f32x2 mixp(unsigned c, unsigned pv, unsigned nv, f32x2 m1, f32x2 m2) {
;     const float c0 = bflo(c), c1 = bfhi(c);
;     float r0 = __builtin_fmaf(m2.x, bflo(nv) - c0, __builtin_fmaf(m1.x, bflo(pv) - c0, c0)), r1 = __builtin_fmaf(m2.y, bfhi(nv) - c1, __builtin_fmaf(m1.y, bfhi(pv) - c1, c1));
;     asm("" : "+v"(r0), "+v"(r1));
;     return (f32x2){r0, r1};
; }
; __device__ __forceinline__ void mix8p(const u32x4 c, const u32x4 pv, const u32x4 nv, const LAS float* mp, const LAS float* mn, float* o) {
;     const f32x4 a0 = *(const LAS f32x4*)mp, a1 = *(const LAS f32x4*)(mp + 4), b0 = *(const LAS f32x4*)mn, b1 = *(const LAS f32x4*)(mn + 4);
;     const f32x2 r0 = mixp(c.x, pv.x, nv.x, (f32x2){a0.x, a0.y}, (f32x2){b0.x, b0.y}), r1 = mixp(c.y, pv.y, nv.y, (f32x2){a0.z, a0.w}, (f32x2){b0.z, b0.w});
;     const f32x2 r2 = mixp(c.z, pv.z, nv.z, (f32x2){a1.x, a1.y}, (f32x2){b1.x, b1.y}), r3 = mixp(c.w, pv.w, nv.w, (f32x2){a1.z, a1.w}, (f32x2){b1.z, b1.w});
;     o[0] = r0.x; o[1] = r0.y; o[2] = r1.x; o[3] = r1.y; o[4] = r2.x; o[5] = r2.y; o[6] = r3.x; o[7] = r3.y;
; }
; __device__ __forceinline__ void prep_x(int l, int b, int h, int dir, int c, LAS float* rg, const LAS float* cst, int lane) {
;     ...
;     bf16x8 bd[2];
; #pragma unroll
;     for (int ks = 0; ks < 2; ++ks) {
;         float o[8]; const int cc = 64 * dir + 32 * ks + 8 * fq;
;         ZERO_ENDS4(cdr[ks]);
;         mix8p(cdr[ks][0], cdr[ks][1], cdr[ks][2], cst + C_CMP + cc, cst + C_CMN + cc, o);
; #pragma unroll
;         for (int i = 0; i < 8; ++i) o[i] = 1.0f - 2.0f * __builtin_amdgcn_rcpf(1.0f + __expf(2.0f * o[i]));
;         bd[ks] = pack8(o);
;     }
.LBB0_399:
	v_add_u32_e32 v2, s8, v156
	v_lshl_add_u32 v2, v2, 2, 0
	s_waitcnt vmcnt(23)
	v_cndmask_b32_e64 v156, v114, 0, s[50:51]
	v_add_u32_e32 v219, 0x24800, v2
	v_cndmask_b32_e64 v109, v117, 0, s[50:51]
	v_cndmask_b32_e64 v154, v116, 0, s[50:51]
	v_cndmask_b32_e64 v155, v115, 0, s[50:51]
	s_waitcnt vmcnt(21)
	v_cndmask_b32_e64 v158, 0, v113, s[52:53]
	v_cndmask_b32_e64 v159, 0, v112, s[52:53]
	v_cndmask_b32_e64 v170, 0, v111, s[52:53]
	v_cndmask_b32_e64 v171, 0, v110, s[52:53]
	v_add_u32_e32 v2, 0x24c00, v2
	ds_read_b128 v[110:113], v219
	ds_read_b128 v[114:117], v219 offset:16
	ds_read_b128 v[224:227], v2
	ds_read_b128 v[228:231], v2 offset:16
	v_lshlrev_b32_e32 v233, 16, v68
	v_lshlrev_b32_e32 v234, 16, v156
	v_lshlrev_b32_e32 v232, 16, v171
	v_sub_f32_e32 v234, v234, v233
	v_and_b32_e32 v68, 0xffff0000, v68
	v_and_b32_e32 v156, 0xffff0000, v156
	v_sub_f32_e32 v232, v232, v233
	s_waitcnt lgkmcnt(3)
	v_fmac_f32_e32 v233, v110, v234
	v_and_b32_e32 v110, 0xffff0000, v171
	v_sub_f32_e32 v156, v156, v68
	v_sub_f32_e32 v110, v110, v68
	v_fmac_f32_e32 v68, v111, v156
	v_lshlrev_b32_e32 v111, 16, v69
	v_lshlrev_b32_e32 v156, 16, v155
	s_waitcnt lgkmcnt(1)
	v_fmac_f32_e32 v68, v225, v110
	v_lshlrev_b32_e32 v110, 16, v170
	v_sub_f32_e32 v156, v156, v111
	v_sub_f32_e32 v110, v110, v111
	v_fmac_f32_e32 v111, v112, v156
	v_and_b32_e32 v69, 0xffff0000, v69
	v_and_b32_e32 v112, 0xffff0000, v155
	v_fmac_f32_e32 v111, v226, v110
	v_and_b32_e32 v110, 0xffff0000, v170
	v_sub_f32_e32 v112, v112, v69
	v_sub_f32_e32 v110, v110, v69
	v_fmac_f32_e32 v69, v113, v112
	v_lshlrev_b32_e32 v112, 16, v70
	v_lshlrev_b32_e32 v113, 16, v154
	v_fmac_f32_e32 v69, v227, v110
	v_lshlrev_b32_e32 v110, 16, v159
	v_sub_f32_e32 v113, v113, v112
	v_sub_f32_e32 v110, v110, v112
	v_fmac_f32_e32 v112, v114, v113
	s_waitcnt lgkmcnt(0)
	v_fmac_f32_e32 v112, v228, v110
	v_and_b32_e32 v110, 0xffff0000, v70
	v_and_b32_e32 v113, 0xffff0000, v154
	v_and_b32_e32 v70, 0xffff0000, v159
	v_sub_f32_e32 v113, v113, v110
	v_sub_f32_e32 v70, v70, v110
	v_fmac_f32_e32 v110, v115, v113
	v_lshlrev_b32_e32 v113, 16, v71
	v_lshlrev_b32_e32 v114, 16, v109
	v_fmac_f32_e32 v110, v229, v70
	v_lshlrev_b32_e32 v70, 16, v158
	v_sub_f32_e32 v114, v114, v113
	v_sub_f32_e32 v70, v70, v113
	v_fmac_f32_e32 v113, v116, v114
	v_and_b32_e32 v114, 0xffff0000, v71
	v_and_b32_e32 v71, 0xffff0000, v109
	v_fmac_f32_e32 v233, v224, v232
	v_fmac_f32_e32 v113, v230, v70
	v_and_b32_e32 v70, 0xffff0000, v158
	s_nop 0
	v_pk_add_f32 v[70:71], v[70:71], v[114:115] op_sel_hi:[1,0] neg_lo:[0,1] neg_hi:[0,1]
	v_fmac_f32_e32 v114, v117, v71
	v_fmac_f32_e32 v114, v231, v70
	v_mul_f32_e32 v70, 0x4038aa3b, v233
	v_mul_f32_e32 v68, 0x4038aa3b, v68
	v_exp_f32_e32 v70, v70
	v_exp_f32_e32 v71, v68
	v_add_f32_e32 v68, 1.0, v70
	v_add_f32_e32 v70, 1.0, v71
	v_mul_f32_e32 v71, 0x4038aa3b, v111
	v_mul_f32_e32 v69, 0x4038aa3b, v69
	v_exp_f32_e32 v71, v71
	v_exp_f32_e32 v109, v69
	v_rcp_f32_e32 v69, v70
	v_add_f32_e32 v70, 1.0, v71
	v_add_f32_e32 v71, 1.0, v109
	v_mul_f32_e32 v109, 0x4038aa3b, v112
	v_exp_f32_e32 v109, v109
	v_mul_f32_e32 v110, 0x4038aa3b, v110
	v_exp_f32_e32 v111, v110
	v_add_f32_e32 v109, 1.0, v109
	v_rcp_f32_e32 v110, v109
	v_add_f32_e32 v109, 1.0, v111
	v_mul_f32_e32 v111, 0x4038aa3b, v113
	v_exp_f32_e32 v112, v111
	v_mul_f32_e32 v111, 0x4038aa3b, v114
	v_exp_f32_e32 v113, v111
	v_rcp_f32_e32 v111, v109
	v_add_f32_e32 v109, 1.0, v112
	v_rcp_f32_e32 v112, v109
	v_add_f32_e32 v109, 1.0, v113
	v_rcp_f32_e32 v68, v68
	v_rcp_f32_e32 v70, v70
	v_rcp_f32_e32 v71, v71
	v_rcp_f32_e32 v113, v109
	v_pk_fma_f32 v[68:69], v[68:69], 2.0, 1.0 op_sel_hi:[1,0,0] neg_lo:[1,0,0] neg_hi:[1,0,0]
	v_pk_fma_f32 v[110:111], v[110:111], 2.0, 1.0 op_sel_hi:[1,0,0] neg_lo:[1,0,0] neg_hi:[1,0,0]
	v_pk_fma_f32 v[70:71], v[70:71], 2.0, 1.0 op_sel_hi:[1,0,0] neg_lo:[1,0,0] neg_hi:[1,0,0]
	v_pk_fma_f32 v[112:113], v[112:113], 2.0, 1.0 op_sel_hi:[1,0,0] neg_lo:[1,0,0] neg_hi:[1,0,0]
	v_cvt_pk_bf16_f32 v68, v68, v69
	v_cvt_pk_bf16_f32 v69, v70, v71
	v_cvt_pk_bf16_f32 v70, v110, v111
	v_cvt_pk_bf16_f32 v71, v112, v113
	v_cndmask_b32_e64 v109, v107, 0, s[50:51]
	v_cndmask_b32_e64 v154, v106, 0, s[50:51]
	v_cndmask_b32_e64 v155, v105, 0, s[50:51]
	v_cndmask_b32_e64 v156, v104, 0, s[50:51]
	s_waitcnt vmcnt(20)
; __device__ __forceinline__ bf16x8 pack8(const float* f) { return __builtin_bit_cast(bf16x8, pack8u(f)); }
; #define MFMA16(a, b, c) __builtin_amdgcn_mfma_f32_16x16x32_bf16((a), (b), (c), 0, 0, 0)
; #define ZERO_ENDS4(A) do { if (!pz) A[1] = (u32x4){0u, 0u, 0u, 0u}; if (!nz) A[2] = (u32x4){0u, 0u, 0u, 0u}; } while (0)
; __device__ __forceinline__ void prep_x(int l, int b, int h, int dir, int c, LAS float* rg, const LAS float* cst, int lane) {
;     ...
;     bf16x8 bd[2];
; #pragma unroll
;     for (int ks = 0; ks < 2; ++ks) {
;         float o[8]; const int cc = 64 * dir + 32 * ks + 8 * fq;
;         ZERO_ENDS4(cdr[ks]);
;         mix8p(cdr[ks][0], cdr[ks][1], cdr[ks][2], cst + C_CMP + cc, cst + C_CMN + cc, o);
; #pragma unroll
;         for (int i = 0; i < 8; ++i) o[i] = 1.0f - 2.0f * __builtin_amdgcn_rcpf(1.0f + __expf(2.0f * o[i]));
;         bd[ks] = pack8(o);
;     }
;     const bf16x8 bv = __builtin_bit_cast(bf16x8, bvr);
; #pragma unroll
;     for (int nb = 0; nb < 4; ++nb) {
;         f32x4 aD = {0.f, 0.f, 0.f, 0.f}, aV = aD;
; #pragma unroll
;         for (int ks = 0; ks < 2; ++ks) aD = MFMA16(__builtin_bit_cast(bf16x8, wdr[nb][ks]), bd[ks], aD);
;         if (l > 0) aV = MFMA16(__builtin_bit_cast(bf16x8, wvr[nb]), bv, aV);
	v_cndmask_b32_e64 v158, 0, v103, s[52:53]
	v_cndmask_b32_e64 v159, 0, v102, s[52:53]
	v_cndmask_b32_e64 v170, 0, v101, s[52:53]
	v_cndmask_b32_e64 v171, 0, v100, s[52:53]
	ds_read_b128 v[100:103], v219 offset:128
	ds_read_b128 v[104:107], v219 offset:144
	ds_read_b128 v[110:113], v2 offset:128
	ds_read_b128 v[114:117], v2 offset:144
	v_lshlrev_b32_e32 v219, 16, v84
	v_lshlrev_b32_e32 v224, 16, v156
	v_lshlrev_b32_e32 v2, 16, v171
	v_sub_f32_e32 v224, v224, v219
	v_sub_f32_e32 v2, v2, v219
	s_waitcnt lgkmcnt(3)
	v_fmac_f32_e32 v219, v100, v224
	s_waitcnt lgkmcnt(1)
	v_fmac_f32_e32 v219, v110, v2
	v_and_b32_e32 v2, 0xffff0000, v84
	v_and_b32_e32 v100, 0xffff0000, v156
	v_and_b32_e32 v84, 0xffff0000, v171
	v_sub_f32_e32 v100, v100, v2
	v_sub_f32_e32 v84, v84, v2
	v_fmac_f32_e32 v2, v101, v100
	v_lshlrev_b32_e32 v100, 16, v85
	v_lshlrev_b32_e32 v101, 16, v155
	v_fmac_f32_e32 v2, v111, v84
	v_lshlrev_b32_e32 v84, 16, v170
	v_sub_f32_e32 v101, v101, v100
	v_sub_f32_e32 v84, v84, v100
	v_fmac_f32_e32 v100, v102, v101
	v_and_b32_e32 v85, 0xffff0000, v85
	v_and_b32_e32 v101, 0xffff0000, v155
	v_fmac_f32_e32 v100, v112, v84
	v_and_b32_e32 v84, 0xffff0000, v170
	v_sub_f32_e32 v101, v101, v85
	v_sub_f32_e32 v84, v84, v85
	v_fmac_f32_e32 v85, v103, v101
	v_lshlrev_b32_e32 v101, 16, v86
	v_lshlrev_b32_e32 v102, 16, v154
	v_fmac_f32_e32 v85, v113, v84
	v_lshlrev_b32_e32 v84, 16, v159
	v_sub_f32_e32 v102, v102, v101
	v_sub_f32_e32 v84, v84, v101
	v_fmac_f32_e32 v101, v104, v102
	v_and_b32_e32 v102, 0xffff0000, v86
	v_and_b32_e32 v86, 0xffff0000, v154
	s_waitcnt lgkmcnt(0)
	v_fmac_f32_e32 v101, v114, v84
	v_and_b32_e32 v84, 0xffff0000, v159
	v_sub_f32_e32 v86, v86, v102
	v_sub_f32_e32 v84, v84, v102
	v_fmac_f32_e32 v102, v105, v86
	v_lshlrev_b32_e32 v103, 16, v87
	v_lshlrev_b32_e32 v86, 16, v109
	v_fmac_f32_e32 v102, v115, v84
	v_lshlrev_b32_e32 v84, 16, v158
	v_sub_f32_e32 v86, v86, v103
	v_sub_f32_e32 v84, v84, v103
	v_fmac_f32_e32 v103, v106, v86
	v_and_b32_e32 v104, 0xffff0000, v87
	v_and_b32_e32 v86, 0xffff0000, v109
	v_fmac_f32_e32 v103, v116, v84
	v_and_b32_e32 v84, 0xffff0000, v158
	v_sub_f32_e32 v86, v86, v104
	v_sub_f32_e32 v84, v84, v104
	v_fmac_f32_e32 v104, v107, v86
	v_mul_f32_e32 v2, 0x4038aa3b, v2
	v_exp_f32_e32 v2, v2
	v_mul_f32_e32 v86, 0x4038aa3b, v100
	v_exp_f32_e32 v86, v86
	v_mul_f32_e32 v85, 0x4038aa3b, v85
	v_exp_f32_e32 v87, v85
	v_add_f32_e32 v2, 1.0, v2
	v_rcp_f32_e32 v85, v2
	v_add_f32_e32 v2, 1.0, v86
	v_rcp_f32_e32 v86, v2
	v_add_f32_e32 v2, 1.0, v87
	v_mul_f32_e32 v87, 0x4038aa3b, v101
	v_exp_f32_e32 v100, v87
	v_mul_f32_e32 v87, 0x4038aa3b, v102
	v_exp_f32_e32 v101, v87
	v_fmac_f32_e32 v104, v117, v84
	v_rcp_f32_e32 v87, v2
	v_add_f32_e32 v2, 1.0, v100
	v_rcp_f32_e32 v100, v2
	v_add_f32_e32 v2, 1.0, v101
	v_mul_f32_e32 v101, 0x4038aa3b, v103
	v_exp_f32_e32 v102, v101
	v_mul_f32_e32 v84, 0x4038aa3b, v219
	v_mul_f32_e32 v101, 0x4038aa3b, v104
	v_exp_f32_e32 v84, v84
	v_exp_f32_e32 v103, v101
	v_rcp_f32_e32 v101, v2
	v_add_f32_e32 v2, 1.0, v102
	v_add_f32_e32 v84, 1.0, v84
	v_rcp_f32_e32 v102, v2
	v_add_f32_e32 v2, 1.0, v103
	v_rcp_f32_e32 v84, v84
	v_rcp_f32_e32 v103, v2
	s_waitcnt vmcnt(19)
	v_mfma_f32_16x16x32_bf16 v[96:99], v[96:99], v[68:71], 0
	v_fma_f32 v86, -v86, 2.0, 1.0
	v_fma_f32 v87, -v87, 2.0, 1.0
	v_pk_fma_f32 v[84:85], v[84:85], 2.0, 1.0 op_sel_hi:[1,0,0] neg_lo:[1,0,0] neg_hi:[1,0,0]
	v_pk_fma_f32 v[100:101], v[100:101], 2.0, 1.0 op_sel_hi:[1,0,0] neg_lo:[1,0,0] neg_hi:[1,0,0]
	v_pk_fma_f32 v[102:103], v[102:103], 2.0, 1.0 op_sel_hi:[1,0,0] neg_lo:[1,0,0] neg_hi:[1,0,0]
	v_cvt_pk_bf16_f32 v84, v84, v85
	v_cvt_pk_bf16_f32 v85, v86, v87
	v_cvt_pk_bf16_f32 v86, v100, v101
	v_cvt_pk_bf16_f32 v87, v102, v103
	s_and_b64 vcc, exec, s[48:49]
	v_mov_b32_e32 v109, 0
	s_waitcnt vmcnt(18)
	v_mfma_f32_16x16x32_bf16 v[92:95], v[92:95], v[84:87], v[96:99]
	v_mov_b32_e32 v110, 0
	v_mov_b32_e32 v111, 0
	s_cbranch_vccnz .LBB0_401
	v_mfma_f32_16x16x32_bf16 v[108:111], v[88:91], v[40:43], 0

; #define LAS __attribute__((address_space(3)))
; __device__ __forceinline__ void unpack4(u32x2 u, float* o) { o[0] = bflo(u.x); o[1] = bfhi(u.x); o[2] = bflo(u.y); o[3] = bfhi(u.y); }
; __device__ __forceinline__ float sigm(float x) { return __builtin_amdgcn_rcpf(1.0f + __expf(-x)); }
; #define ZERO_ENDS2(A) do { if (!pz) A[1] = (u32x2){0u, 0u}; if (!nz) A[2] = (u32x2){0u, 0u}; } while (0)
; __device__ __forceinline__ void prep_x(int l, int b, int h, int dir, int c, LAS float* rg, const LAS float* cst, int lane) {
;     ...
;         const int co = nb * 16 + 4 * fq, ch = h * 64 + co;
;         float vv[4];
;         ZERO_ENDS2(vr_[nb]);
;         mix4p(vr_[nb][0], vr_[nb][1], vr_[nb][2], cst + C_RMP + 128 + co, cst + C_RMN + 128 + co, vv);
;         const f32x4 dbias = *(const LAS f32x4*)(cst + C_DB + 64 * dir + co);
;         if (l > 0) {
;             float vf[4]; unpack4(vfr[nb], vf);
;             const f32x4 vbias = *(const LAS f32x4*)(cst + C_VB + co);
; #pragma unroll
;             for (int i = 0; i < 4; ++i) { const float g = sigm(vbias[i] + aV[i]); vv[i] = vv[i] + (vf[i] - vv[i]) * g; }
;         }
.LBB0_419:
	ds_read_b128 v[42:45], v103 offset:192
	ds_read_b128 v[56:59], v104 offset:192
	s_waitcnt vmcnt(1)
	v_cndmask_b32_e64 v20, v20, 0, s[50:51]
	s_waitcnt vmcnt(0)
	v_cndmask_b32_e64 v14, 0, v14, s[52:53]
	v_lshlrev_b32_e32 v26, 16, v14
	v_lshlrev_b32_e32 v40, 16, v10
	v_lshlrev_b32_e32 v27, 16, v20
	v_and_b32_e32 v41, 0xffff0000, v10
	v_and_b32_e32 v10, 0xffff0000, v14
	v_and_b32_e32 v14, 0xffff0000, v20
	v_cndmask_b32_e64 v21, v21, 0, s[50:51]
	s_nop 0
	v_sub_f32_e32 v14, v14, v41
	v_cndmask_b32_e64 v15, 0, v15, s[52:53]
	v_pk_add_f32 v[26:27], v[26:27], v[40:41] op_sel_hi:[1,0] neg_lo:[0,1] neg_hi:[0,1]
	s_waitcnt lgkmcnt(1)
	v_fmac_f32_e32 v40, v42, v27
	v_sub_f32_e32 v10, v10, v41
	v_fmac_f32_e32 v41, v43, v14
	v_lshlrev_b32_e32 v42, 16, v11
	v_lshlrev_b32_e32 v14, 16, v21
	s_waitcnt lgkmcnt(0)
	v_fmac_f32_e32 v41, v57, v10
	v_lshlrev_b32_e32 v10, 16, v15
	v_sub_f32_e32 v14, v14, v42
	v_sub_f32_e32 v10, v10, v42
	v_fmac_f32_e32 v42, v44, v14
	v_and_b32_e32 v43, 0xffff0000, v11
	v_and_b32_e32 v11, 0xffff0000, v21
	v_fmac_f32_e32 v42, v58, v10
	v_and_b32_e32 v10, 0xffff0000, v15
	v_sub_f32_e32 v11, v11, v43
	v_sub_f32_e32 v10, v10, v43
	v_fmac_f32_e32 v43, v45, v11
	ds_read_b128 v[44:47], v102 offset:192
	v_fmac_f32_e32 v40, v56, v26
	v_fmac_f32_e32 v43, v59, v10
	s_and_b64 vcc, exec, s[48:49]
	s_cbranch_vccnz .LBB0_421
	v_add_u32_e32 v2, 0x25dc0, v2
	ds_read_b128 v[56:59], v2
	v_and_b32_e32 v11, 0xffff0000, v4
	s_waitcnt lgkmcnt(0)
	v_add_f32_e32 v2, v52, v56
	v_add_f32_e32 v10, v53, v57
	v_mul_f32_e32 v2, 0xbfb8aa3b, v2
	v_mul_f32_e32 v10, 0xbfb8aa3b, v10
	v_exp_f32_e32 v2, v2
	v_exp_f32_e32 v14, v10
	v_lshlrev_b32_e32 v10, 16, v4
	v_pk_add_f32 v[10:11], v[10:11], v[40:41] neg_lo:[0,1] neg_hi:[0,1]
	v_add_f32_e32 v2, 1.0, v2
	v_add_f32_e32 v4, 1.0, v14
	v_rcp_f32_e32 v14, v2
	v_add_f32_e32 v2, v54, v58
	v_rcp_f32_e32 v15, v4
	v_mul_f32_e32 v2, 0xbfb8aa3b, v2
	v_add_f32_e32 v4, v55, v59
	v_exp_f32_e32 v2, v2
	v_mul_f32_e32 v4, 0xbfb8aa3b, v4
	v_exp_f32_e32 v4, v4
	v_pk_fma_f32 v[40:41], v[10:11], v[14:15], v[40:41]
	v_add_f32_e32 v2, 1.0, v2
	v_rcp_f32_e32 v10, v2
	v_add_f32_e32 v2, 1.0, v4
	v_rcp_f32_e32 v11, v2
	v_lshlrev_b32_e32 v4, 16, v5
	v_and_b32_e32 v5, 0xffff0000, v5
	v_pk_add_f32 v[4:5], v[4:5], v[42:43] neg_lo:[0,1] neg_hi:[0,1]
	s_nop 0
	v_pk_fma_f32 v[42:43], v[4:5], v[10:11], v[42:43]
